# GEMM mainloops: mid-block setprio 0/1 pair and redundant post-barrier lgkmcnt(0) removed; setprio 1 moved before / setprio 0 after the s_barrier so the MFMA block starts and ends at the barrier
# speedup vs baseline: 1.0044x; 1.0044x over previous
.LBB0_352:
	s_add_u32 s44, s42, 0xfff80080
	s_addc_u32 s45, s43, -1
	s_add_i32 s55, 0, 0x10000
	s_cmp_eq_u32 s54, 28
	s_cselect_b32 s53, s17, s45
	s_cselect_b32 s52, s18, s44
	v_add_u32_e32 v150, s55, v158
	s_cselect_b32 s45, s5, s33
	s_cselect_b32 s44, s20, s28
	s_add_i32 s61, 0, 0x14000
	ds_read_b128 v[130:133], v150
	ds_read_b128 v[160:163], v150 offset:1024
	ds_read_b128 v[164:167], v150 offset:2048
	ds_read_b128 v[168:171], v150 offset:3072
	v_add_u32_e32 v150, s61, v158
	ds_read_b128 v[172:175], v150
	ds_read_b128 v[176:179], v150 offset:1024
	ds_read_b128 v[180:183], v150 offset:2048
	ds_read_b128 v[184:187], v150 offset:3072
	v_lshl_add_u64 v[150:151], s[42:43], 0, v[146:147]
	s_add_i32 m0, s35, 0xc000
	ds_read_b128 v[188:191], v159
	ds_read_b128 v[192:195], v159 offset:1024
	ds_read_b128 v[196:199], v159 offset:2048
	ds_read_b128 v[210:213], v159 offset:3072
	ds_read_b128 v[214:217], v159 offset:4096
	ds_read_b128 v[218:221], v159 offset:5120
	ds_read_b128 v[222:225], v159 offset:6144
	ds_read_b128 v[226:229], v159 offset:7168
	global_load_lds_dwordx4 v[150:151], off
	v_lshl_add_u64 v[150:151], s[42:43], 0, v[148:149]
	s_add_i32 m0, s35, 0xe000
	s_nop 0
	global_load_lds_dwordx4 v[150:151], off
	s_waitcnt vmcnt(8)
	s_waitcnt lgkmcnt(0)
	s_setprio 1
	s_barrier
	v_mfma_f32_16x16x32_bf16 v[126:129], v[130:133], v[188:191], v[126:129]
	v_mfma_f32_16x16x32_bf16 v[122:125], v[164:167], v[188:191], v[122:125]
	v_mfma_f32_16x16x32_bf16 v[110:113], v[130:133], v[196:199], v[110:113]
	v_mfma_f32_16x16x32_bf16 v[106:109], v[164:167], v[196:199], v[106:109]
	v_mfma_f32_16x16x32_bf16 v[92:95], v[130:133], v[214:217], v[92:95]
	v_mfma_f32_16x16x32_bf16 v[88:91], v[164:167], v[214:217], v[88:91]
	v_mfma_f32_16x16x32_bf16 v[76:79], v[130:133], v[222:225], v[76:79]
	v_mfma_f32_16x16x32_bf16 v[72:75], v[164:167], v[222:225], v[72:75]
	v_mfma_f32_16x16x32_bf16 v[126:129], v[160:163], v[192:195], v[126:129]
	v_mfma_f32_16x16x32_bf16 v[122:125], v[168:171], v[192:195], v[122:125]
	v_mfma_f32_16x16x32_bf16 v[110:113], v[160:163], v[210:213], v[110:113]
	v_mfma_f32_16x16x32_bf16 v[106:109], v[168:171], v[210:213], v[106:109]
	v_mfma_f32_16x16x32_bf16 v[92:95], v[160:163], v[218:221], v[92:95]
	v_mfma_f32_16x16x32_bf16 v[88:91], v[168:171], v[218:221], v[88:91]
	v_mfma_f32_16x16x32_bf16 v[76:79], v[160:163], v[226:229], v[76:79]
	v_mfma_f32_16x16x32_bf16 v[72:75], v[168:171], v[226:229], v[72:75]
	v_mfma_f32_16x16x32_bf16 v[118:121], v[172:175], v[188:191], v[118:121]
	v_mfma_f32_16x16x32_bf16 v[114:117], v[180:183], v[188:191], v[114:117]
	v_mfma_f32_16x16x32_bf16 v[102:105], v[172:175], v[196:199], v[102:105]
	v_mfma_f32_16x16x32_bf16 v[98:101], v[180:183], v[196:199], v[98:101]
	v_mfma_f32_16x16x32_bf16 v[84:87], v[172:175], v[214:217], v[84:87]
	v_mfma_f32_16x16x32_bf16 v[80:83], v[180:183], v[214:217], v[80:83]
	v_mfma_f32_16x16x32_bf16 v[68:71], v[172:175], v[222:225], v[68:71]
	v_mfma_f32_16x16x32_bf16 v[64:67], v[180:183], v[222:225], v[64:67]
	v_mfma_f32_16x16x32_bf16 v[118:121], v[176:179], v[192:195], v[118:121]
	v_mfma_f32_16x16x32_bf16 v[114:117], v[184:187], v[192:195], v[114:117]
	v_mfma_f32_16x16x32_bf16 v[102:105], v[176:179], v[210:213], v[102:105]
	v_mfma_f32_16x16x32_bf16 v[98:101], v[184:187], v[210:213], v[98:101]
	v_mfma_f32_16x16x32_bf16 v[84:87], v[176:179], v[218:221], v[84:87]
	v_mfma_f32_16x16x32_bf16 v[80:83], v[184:187], v[218:221], v[80:83]
	v_mfma_f32_16x16x32_bf16 v[68:71], v[176:179], v[226:229], v[68:71]
	v_mfma_f32_16x16x32_bf16 v[64:67], v[184:187], v[226:229], v[64:67]
	s_barrier
	s_setprio 0
	s_add_i32 s55, s55, s75
	v_lshl_add_u64 v[150:151], s[44:45], 0, v[142:143]
	s_mov_b32 m0, s55
	ds_read_b128 v[188:191], v159 offset:16384
	ds_read_b128 v[192:195], v159 offset:17408
	ds_read_b128 v[196:199], v159 offset:18432
	ds_read_b128 v[210:213], v159 offset:19456
	ds_read_b128 v[214:217], v159 offset:20480
	ds_read_b128 v[218:221], v159 offset:21504
	ds_read_b128 v[222:225], v159 offset:22528
	ds_read_b128 v[226:229], v159 offset:23552
	global_load_lds_dwordx4 v[150:151], off
	s_add_i32 m0, s55, 0x2000
	s_add_u32 s56, s44, 0x80000
	v_lshl_add_u64 v[154:155], s[44:45], 0, v[138:139]
	s_addc_u32 s57, s45, 0
	s_add_i32 s55, s61, s75
	global_load_lds_dwordx4 v[154:155], off
	v_lshl_add_u64 v[156:157], s[56:57], 0, v[142:143]
	s_mov_b32 m0, s55
	v_lshl_add_u64 v[202:203], s[52:53], 0, v[140:141]
	global_load_lds_dwordx4 v[156:157], off
	v_lshl_add_u64 v[156:157], s[56:57], 0, v[138:139]
	s_add_i32 m0, s55, 0x2000
	s_nop 0
	global_load_lds_dwordx4 v[156:157], off
	v_lshl_add_u64 v[156:157], s[52:53], 0, v[144:145]
	s_mov_b32 m0, s35
	s_nop 0
	global_load_lds_dwordx4 v[156:157], off
	s_mov_b32 m0, s68
	s_nop 0
	global_load_lds_dwordx4 v[202:203], off
	s_waitcnt vmcnt(8)
	s_waitcnt lgkmcnt(0)
	s_setprio 1
	s_barrier
	v_mfma_f32_16x16x32_bf16 v[60:63], v[130:133], v[188:191], v[60:63]
	v_mfma_f32_16x16x32_bf16 v[56:59], v[164:167], v[188:191], v[56:59]
	v_mfma_f32_16x16x32_bf16 v[44:47], v[130:133], v[196:199], v[44:47]
	v_mfma_f32_16x16x32_bf16 v[40:43], v[164:167], v[196:199], v[40:43]
	v_mfma_f32_16x16x32_bf16 v[28:31], v[130:133], v[214:217], v[28:31]
	v_mfma_f32_16x16x32_bf16 v[24:27], v[164:167], v[214:217], v[24:27]
	v_mfma_f32_16x16x32_bf16 v[12:15], v[130:133], v[222:225], v[12:15]
	v_mfma_f32_16x16x32_bf16 v[8:11], v[164:167], v[222:225], v[8:11]
	v_mfma_f32_16x16x32_bf16 v[60:63], v[160:163], v[192:195], v[60:63]
	v_mfma_f32_16x16x32_bf16 v[56:59], v[168:171], v[192:195], v[56:59]
	v_mfma_f32_16x16x32_bf16 v[44:47], v[160:163], v[210:213], v[44:47]
	v_mfma_f32_16x16x32_bf16 v[40:43], v[168:171], v[210:213], v[40:43]
	v_mfma_f32_16x16x32_bf16 v[28:31], v[160:163], v[218:221], v[28:31]
	v_mfma_f32_16x16x32_bf16 v[24:27], v[168:171], v[218:221], v[24:27]
	v_mfma_f32_16x16x32_bf16 v[12:15], v[160:163], v[226:229], v[12:15]
	v_mfma_f32_16x16x32_bf16 v[8:11], v[168:171], v[226:229], v[8:11]
	v_mfma_f32_16x16x32_bf16 v[52:55], v[172:175], v[188:191], v[52:55]
	v_mfma_f32_16x16x32_bf16 v[48:51], v[180:183], v[188:191], v[48:51]
	v_mfma_f32_16x16x32_bf16 v[36:39], v[172:175], v[196:199], v[36:39]
	v_mfma_f32_16x16x32_bf16 v[32:35], v[180:183], v[196:199], v[32:35]
	v_mfma_f32_16x16x32_bf16 v[20:23], v[172:175], v[214:217], v[20:23]
	v_mfma_f32_16x16x32_bf16 v[16:19], v[180:183], v[214:217], v[16:19]
	v_mfma_f32_16x16x32_bf16 v[4:7], v[172:175], v[222:225], v[4:7]
	v_mfma_f32_16x16x32_bf16 v[0:3], v[180:183], v[222:225], v[0:3]
	v_mfma_f32_16x16x32_bf16 v[52:55], v[176:179], v[192:195], v[52:55]
	v_mfma_f32_16x16x32_bf16 v[48:51], v[184:187], v[192:195], v[48:51]
	v_mfma_f32_16x16x32_bf16 v[36:39], v[176:179], v[210:213], v[36:39]
	v_mfma_f32_16x16x32_bf16 v[32:35], v[184:187], v[210:213], v[32:35]
	v_mfma_f32_16x16x32_bf16 v[20:23], v[176:179], v[218:221], v[20:23]
	v_mfma_f32_16x16x32_bf16 v[16:19], v[184:187], v[218:221], v[16:19]
	v_mfma_f32_16x16x32_bf16 v[4:7], v[176:179], v[226:229], v[4:7]
	v_mfma_f32_16x16x32_bf16 v[0:3], v[184:187], v[226:229], v[0:3]
	s_barrier
	s_setprio 0
	s_add_i32 s55, 0, 0x18000
	s_add_i32 s56, 0, 0x1c000
	v_add_u32_e32 v168, s55, v158
	v_add_u32_e32 v184, s56, v158
	ds_read_b128 v[130:133], v168
	ds_read_b128 v[160:163], v168 offset:1024
	ds_read_b128 v[164:167], v168 offset:2048
	ds_read_b128 v[168:171], v168 offset:3072
	ds_read_b128 v[172:175], v184
	ds_read_b128 v[176:179], v184 offset:1024
	ds_read_b128 v[180:183], v184 offset:2048
	ds_read_b128 v[184:187], v184 offset:3072
	s_add_u32 s52, s52, 0x80000
	s_addc_u32 s53, s53, 0
	s_mov_b32 m0, s69
	v_lshl_add_u64 v[204:205], s[52:53], 0, v[144:145]
	ds_read_b128 v[188:191], v159 offset:32768
	ds_read_b128 v[192:195], v159 offset:33792
	ds_read_b128 v[196:199], v159 offset:34816
	ds_read_b128 v[210:213], v159 offset:35840
	ds_read_b128 v[214:217], v159 offset:36864
	ds_read_b128 v[218:221], v159 offset:37888
	ds_read_b128 v[222:225], v159 offset:38912
	ds_read_b128 v[226:229], v159 offset:39936
	global_load_lds_dwordx4 v[204:205], off
	v_lshl_add_u64 v[204:205], s[52:53], 0, v[140:141]
	s_mov_b32 m0, s77
	s_nop 0
	global_load_lds_dwordx4 v[204:205], off
	s_waitcnt vmcnt(8)
	s_waitcnt lgkmcnt(0)
	s_setprio 1
	s_barrier
	v_mfma_f32_16x16x32_bf16 v[126:129], v[130:133], v[188:191], v[126:129]
	v_mfma_f32_16x16x32_bf16 v[122:125], v[164:167], v[188:191], v[122:125]
	v_mfma_f32_16x16x32_bf16 v[110:113], v[130:133], v[196:199], v[110:113]
	v_mfma_f32_16x16x32_bf16 v[106:109], v[164:167], v[196:199], v[106:109]
	v_mfma_f32_16x16x32_bf16 v[92:95], v[130:133], v[214:217], v[92:95]
	v_mfma_f32_16x16x32_bf16 v[88:91], v[164:167], v[214:217], v[88:91]
	v_mfma_f32_16x16x32_bf16 v[76:79], v[130:133], v[222:225], v[76:79]
	v_mfma_f32_16x16x32_bf16 v[72:75], v[164:167], v[222:225], v[72:75]
	v_mfma_f32_16x16x32_bf16 v[126:129], v[160:163], v[192:195], v[126:129]
	v_mfma_f32_16x16x32_bf16 v[122:125], v[168:171], v[192:195], v[122:125]
	v_mfma_f32_16x16x32_bf16 v[110:113], v[160:163], v[210:213], v[110:113]
	v_mfma_f32_16x16x32_bf16 v[106:109], v[168:171], v[210:213], v[106:109]
	v_mfma_f32_16x16x32_bf16 v[92:95], v[160:163], v[218:221], v[92:95]
	v_mfma_f32_16x16x32_bf16 v[88:91], v[168:171], v[218:221], v[88:91]
	v_mfma_f32_16x16x32_bf16 v[76:79], v[160:163], v[226:229], v[76:79]
	v_mfma_f32_16x16x32_bf16 v[72:75], v[168:171], v[226:229], v[72:75]
	v_mfma_f32_16x16x32_bf16 v[118:121], v[172:175], v[188:191], v[118:121]
	v_mfma_f32_16x16x32_bf16 v[114:117], v[180:183], v[188:191], v[114:117]
	v_mfma_f32_16x16x32_bf16 v[102:105], v[172:175], v[196:199], v[102:105]
	v_mfma_f32_16x16x32_bf16 v[98:101], v[180:183], v[196:199], v[98:101]
	v_mfma_f32_16x16x32_bf16 v[84:87], v[172:175], v[214:217], v[84:87]
	v_mfma_f32_16x16x32_bf16 v[80:83], v[180:183], v[214:217], v[80:83]
	v_mfma_f32_16x16x32_bf16 v[68:71], v[172:175], v[222:225], v[68:71]
	v_mfma_f32_16x16x32_bf16 v[64:67], v[180:183], v[222:225], v[64:67]
	v_mfma_f32_16x16x32_bf16 v[118:121], v[176:179], v[192:195], v[118:121]
	v_mfma_f32_16x16x32_bf16 v[114:117], v[184:187], v[192:195], v[114:117]
	v_mfma_f32_16x16x32_bf16 v[102:105], v[176:179], v[210:213], v[102:105]
	v_mfma_f32_16x16x32_bf16 v[98:101], v[184:187], v[210:213], v[98:101]
	v_mfma_f32_16x16x32_bf16 v[84:87], v[176:179], v[218:221], v[84:87]
	v_mfma_f32_16x16x32_bf16 v[80:83], v[184:187], v[218:221], v[80:83]
	v_mfma_f32_16x16x32_bf16 v[68:71], v[176:179], v[226:229], v[68:71]
	v_mfma_f32_16x16x32_bf16 v[64:67], v[184:187], v[226:229], v[64:67]
	s_barrier
	s_setprio 0
	s_add_i32 s52, s55, s75
	v_lshl_add_u64 v[150:151], v[150:151], 0, s[64:65]
	s_mov_b32 m0, s52
	ds_read_b128 v[188:191], v159 offset:49152
	ds_read_b128 v[192:195], v159 offset:50176
	ds_read_b128 v[196:199], v159 offset:51200
	ds_read_b128 v[210:213], v159 offset:52224
	ds_read_b128 v[214:217], v159 offset:53248
	ds_read_b128 v[218:221], v159 offset:54272
	ds_read_b128 v[222:225], v159 offset:55296
	ds_read_b128 v[226:229], v159 offset:56320
	global_load_lds_dwordx4 v[150:151], off
	s_add_i32 m0, s52, 0x2000
	s_add_u32 s44, s44, 0x80080
	v_lshl_add_u64 v[150:151], v[154:155], 0, s[64:65]
	s_addc_u32 s45, s45, 0
	s_add_i32 s52, s56, s75
	global_load_lds_dwordx4 v[150:151], off
	v_lshl_add_u64 v[150:151], s[44:45], 0, v[142:143]
	s_mov_b32 m0, s52
	s_nop 0
	global_load_lds_dwordx4 v[150:151], off
	v_lshl_add_u64 v[150:151], s[44:45], 0, v[138:139]
	s_add_i32 m0, s52, 0x2000
	s_nop 0
	global_load_lds_dwordx4 v[150:151], off
	v_lshl_add_u64 v[150:151], v[156:157], 0, s[64:65]
	s_mov_b32 m0, s79
	s_nop 0
	global_load_lds_dwordx4 v[150:151], off
	v_lshl_add_u64 v[150:151], v[202:203], 0, s[64:65]
	s_mov_b32 m0, s81
	s_nop 0
	global_load_lds_dwordx4 v[150:151], off
	s_waitcnt vmcnt(8)
	s_waitcnt lgkmcnt(0)
	s_setprio 1
	s_barrier
	v_mfma_f32_16x16x32_bf16 v[60:63], v[130:133], v[188:191], v[60:63]
	v_mfma_f32_16x16x32_bf16 v[56:59], v[164:167], v[188:191], v[56:59]
	v_mfma_f32_16x16x32_bf16 v[44:47], v[130:133], v[196:199], v[44:47]
	v_mfma_f32_16x16x32_bf16 v[40:43], v[164:167], v[196:199], v[40:43]
	v_mfma_f32_16x16x32_bf16 v[28:31], v[130:133], v[214:217], v[28:31]
	v_mfma_f32_16x16x32_bf16 v[24:27], v[164:167], v[214:217], v[24:27]
	v_mfma_f32_16x16x32_bf16 v[12:15], v[130:133], v[222:225], v[12:15]
	v_mfma_f32_16x16x32_bf16 v[8:11], v[164:167], v[222:225], v[8:11]
	v_mfma_f32_16x16x32_bf16 v[60:63], v[160:163], v[192:195], v[60:63]
	v_mfma_f32_16x16x32_bf16 v[56:59], v[168:171], v[192:195], v[56:59]
	v_mfma_f32_16x16x32_bf16 v[44:47], v[160:163], v[210:213], v[44:47]
	v_mfma_f32_16x16x32_bf16 v[40:43], v[168:171], v[210:213], v[40:43]
	v_mfma_f32_16x16x32_bf16 v[28:31], v[160:163], v[218:221], v[28:31]
	v_mfma_f32_16x16x32_bf16 v[24:27], v[168:171], v[218:221], v[24:27]
	v_mfma_f32_16x16x32_bf16 v[12:15], v[160:163], v[226:229], v[12:15]
	v_mfma_f32_16x16x32_bf16 v[8:11], v[168:171], v[226:229], v[8:11]
	v_mfma_f32_16x16x32_bf16 v[52:55], v[172:175], v[188:191], v[52:55]
	v_mfma_f32_16x16x32_bf16 v[48:51], v[180:183], v[188:191], v[48:51]
	v_mfma_f32_16x16x32_bf16 v[36:39], v[172:175], v[196:199], v[36:39]
	v_mfma_f32_16x16x32_bf16 v[32:35], v[180:183], v[196:199], v[32:35]
	v_mfma_f32_16x16x32_bf16 v[20:23], v[172:175], v[214:217], v[20:23]
	v_mfma_f32_16x16x32_bf16 v[16:19], v[180:183], v[214:217], v[16:19]
	v_mfma_f32_16x16x32_bf16 v[4:7], v[172:175], v[222:225], v[4:7]
	v_mfma_f32_16x16x32_bf16 v[0:3], v[180:183], v[222:225], v[0:3]
	v_mfma_f32_16x16x32_bf16 v[52:55], v[176:179], v[192:195], v[52:55]
	v_mfma_f32_16x16x32_bf16 v[48:51], v[184:187], v[192:195], v[48:51]
	v_mfma_f32_16x16x32_bf16 v[36:39], v[176:179], v[210:213], v[36:39]
	v_mfma_f32_16x16x32_bf16 v[32:35], v[184:187], v[210:213], v[32:35]
	v_mfma_f32_16x16x32_bf16 v[20:23], v[176:179], v[218:221], v[20:23]
	v_mfma_f32_16x16x32_bf16 v[16:19], v[184:187], v[218:221], v[16:19]
	v_mfma_f32_16x16x32_bf16 v[4:7], v[176:179], v[226:229], v[4:7]
	v_mfma_f32_16x16x32_bf16 v[0:3], v[184:187], v[226:229], v[0:3]
	s_barrier
	s_setprio 0
	s_add_i32 s54, s54, 2
	s_add_u32 s42, s42, 0x100
	s_addc_u32 s43, s43, 0
	s_add_u32 s28, s28, 0x100
	s_addc_u32 s33, s33, 0
	s_cmp_gt_u32 s54, 29
	s_cbranch_scc0 .LBB0_352
	v_readlane_b32 s6, v251, 54
	v_readlane_b32 s7, v251, 55
	s_and_b64 vcc, exec, s[6:7]
	s_cbranch_vccz .LBB0_355
	s_barrier

.LBB0_636:
	s_add_u32 s56, s68, 0xfffe0080
	s_addc_u32 s57, s69, -1
	s_add_i32 s58, 0, 0x10000
	s_cmp_eq_u32 s55, 4
	s_cselect_b32 s85, s35, s57
	s_cselect_b32 s84, s43, s56
	v_add_u32_e32 v145, s58, v142
	s_cselect_b32 s83, s31, s54
	s_cselect_b32 s82, s50, s51
	s_add_i32 s59, 0, 0x14000
	ds_read_b128 v[146:149], v145
	ds_read_b128 v[150:153], v145 offset:1024
	ds_read_b128 v[158:161], v145 offset:2048
	ds_read_b128 v[162:165], v145 offset:3072
	v_add_u32_e32 v145, s59, v142
	ds_read_b128 v[166:169], v145
	ds_read_b128 v[170:173], v145 offset:1024
	ds_read_b128 v[174:177], v145 offset:2048
	ds_read_b128 v[178:181], v145 offset:3072
	v_lshl_add_u64 v[154:155], s[68:69], 0, v[136:137]
	s_add_i32 m0, s10, 0xc000
	ds_read_b128 v[182:185], v144
	ds_read_b128 v[186:189], v144 offset:1024
	ds_read_b128 v[190:193], v144 offset:2048
	ds_read_b128 v[194:197], v144 offset:3072
	ds_read_b128 v[210:213], v144 offset:4096
	ds_read_b128 v[214:217], v144 offset:5120
	ds_read_b128 v[218:221], v144 offset:6144
	ds_read_b128 v[222:225], v144 offset:7168
	global_load_lds_dwordx4 v[154:155], off
	v_lshl_add_u64 v[154:155], s[68:69], 0, v[138:139]
	s_add_i32 m0, s10, 0xe000
	s_nop 0
	global_load_lds_dwordx4 v[154:155], off
	s_waitcnt vmcnt(8)
	s_waitcnt lgkmcnt(0)
	s_setprio 1
	s_barrier
	v_mfma_f32_16x16x32_bf16 v[126:129], v[146:149], v[182:185], v[126:129]
	v_mfma_f32_16x16x32_bf16 v[122:125], v[158:161], v[182:185], v[122:125]
	v_mfma_f32_16x16x32_bf16 v[118:121], v[146:149], v[190:193], v[118:121]
	v_mfma_f32_16x16x32_bf16 v[114:117], v[158:161], v[190:193], v[114:117]
	v_mfma_f32_16x16x32_bf16 v[102:105], v[146:149], v[210:213], v[102:105]
	v_mfma_f32_16x16x32_bf16 v[98:101], v[158:161], v[210:213], v[98:101]
	v_mfma_f32_16x16x32_bf16 v[84:87], v[146:149], v[218:221], v[84:87]
	v_mfma_f32_16x16x32_bf16 v[80:83], v[158:161], v[218:221], v[80:83]
	v_mfma_f32_16x16x32_bf16 v[126:129], v[150:153], v[186:189], v[126:129]
	v_mfma_f32_16x16x32_bf16 v[122:125], v[162:165], v[186:189], v[122:125]
	v_mfma_f32_16x16x32_bf16 v[118:121], v[150:153], v[194:197], v[118:121]
	v_mfma_f32_16x16x32_bf16 v[114:117], v[162:165], v[194:197], v[114:117]
	v_mfma_f32_16x16x32_bf16 v[102:105], v[150:153], v[214:217], v[102:105]
	v_mfma_f32_16x16x32_bf16 v[98:101], v[162:165], v[214:217], v[98:101]
	v_mfma_f32_16x16x32_bf16 v[84:87], v[150:153], v[222:225], v[84:87]
	v_mfma_f32_16x16x32_bf16 v[80:83], v[162:165], v[222:225], v[80:83]
	v_mfma_f32_16x16x32_bf16 v[110:113], v[166:169], v[182:185], v[110:113]
	v_mfma_f32_16x16x32_bf16 v[106:109], v[174:177], v[182:185], v[106:109]
	v_mfma_f32_16x16x32_bf16 v[92:95], v[166:169], v[190:193], v[92:95]
	v_mfma_f32_16x16x32_bf16 v[88:91], v[174:177], v[190:193], v[88:91]
	v_mfma_f32_16x16x32_bf16 v[76:79], v[166:169], v[210:213], v[76:79]
	v_mfma_f32_16x16x32_bf16 v[72:75], v[174:177], v[210:213], v[72:75]
	v_mfma_f32_16x16x32_bf16 v[68:71], v[166:169], v[218:221], v[68:71]
	v_mfma_f32_16x16x32_bf16 v[64:67], v[174:177], v[218:221], v[64:67]
	v_mfma_f32_16x16x32_bf16 v[110:113], v[170:173], v[186:189], v[110:113]
	v_mfma_f32_16x16x32_bf16 v[106:109], v[178:181], v[186:189], v[106:109]
	v_mfma_f32_16x16x32_bf16 v[92:95], v[170:173], v[194:197], v[92:95]
	v_mfma_f32_16x16x32_bf16 v[88:91], v[178:181], v[194:197], v[88:91]
	v_mfma_f32_16x16x32_bf16 v[76:79], v[170:173], v[214:217], v[76:79]
	v_mfma_f32_16x16x32_bf16 v[72:75], v[178:181], v[214:217], v[72:75]
	v_mfma_f32_16x16x32_bf16 v[68:71], v[170:173], v[222:225], v[68:71]
	v_mfma_f32_16x16x32_bf16 v[64:67], v[178:181], v[222:225], v[64:67]
	s_barrier
	s_setprio 0
	s_add_i32 s56, s58, s75
	v_lshl_add_u64 v[154:155], s[82:83], 0, v[96:97]
	s_mov_b32 m0, s56
	ds_read_b128 v[182:185], v144 offset:16384
	ds_read_b128 v[186:189], v144 offset:17408
	ds_read_b128 v[190:193], v144 offset:18432
	ds_read_b128 v[194:197], v144 offset:19456
	ds_read_b128 v[210:213], v144 offset:20480
	ds_read_b128 v[214:217], v144 offset:21504
	ds_read_b128 v[218:221], v144 offset:22528
	ds_read_b128 v[222:225], v144 offset:23552
	global_load_lds_dwordx4 v[154:155], off
	s_add_i32 m0, s56, 0x2000
	s_add_u32 s56, s82, 0x20000
	v_lshl_add_u64 v[156:157], s[82:83], 0, v[130:131]
	s_addc_u32 s57, s83, 0
	s_add_i32 s58, s59, s75
	global_load_lds_dwordx4 v[156:157], off
	v_lshl_add_u64 v[198:199], s[56:57], 0, v[96:97]
	s_mov_b32 m0, s58
	v_lshl_add_u64 v[202:203], s[84:85], 0, v[132:133]
	global_load_lds_dwordx4 v[198:199], off
	v_lshl_add_u64 v[198:199], s[56:57], 0, v[130:131]
	s_add_i32 m0, s58, 0x2000
	s_nop 0
	global_load_lds_dwordx4 v[198:199], off
	v_lshl_add_u64 v[198:199], s[84:85], 0, v[134:135]
	s_mov_b32 m0, s10
	s_nop 0
	global_load_lds_dwordx4 v[198:199], off
	s_mov_b32 m0, s12
	s_nop 0
	global_load_lds_dwordx4 v[202:203], off
	s_waitcnt vmcnt(8)
	s_waitcnt lgkmcnt(0)
	s_setprio 1
	s_barrier
	v_mfma_f32_16x16x32_bf16 v[60:63], v[146:149], v[182:185], v[60:63]
	v_mfma_f32_16x16x32_bf16 v[56:59], v[158:161], v[182:185], v[56:59]
	v_mfma_f32_16x16x32_bf16 v[52:55], v[146:149], v[190:193], v[52:55]
	v_mfma_f32_16x16x32_bf16 v[48:51], v[158:161], v[190:193], v[48:51]
	v_mfma_f32_16x16x32_bf16 v[36:39], v[146:149], v[210:213], v[36:39]
	v_mfma_f32_16x16x32_bf16 v[32:35], v[158:161], v[210:213], v[32:35]
	v_mfma_f32_16x16x32_bf16 v[20:23], v[146:149], v[218:221], v[20:23]
	v_mfma_f32_16x16x32_bf16 v[16:19], v[158:161], v[218:221], v[16:19]
	v_mfma_f32_16x16x32_bf16 v[60:63], v[150:153], v[186:189], v[60:63]
	v_mfma_f32_16x16x32_bf16 v[56:59], v[162:165], v[186:189], v[56:59]
	v_mfma_f32_16x16x32_bf16 v[52:55], v[150:153], v[194:197], v[52:55]
	v_mfma_f32_16x16x32_bf16 v[48:51], v[162:165], v[194:197], v[48:51]
	v_mfma_f32_16x16x32_bf16 v[36:39], v[150:153], v[214:217], v[36:39]
	v_mfma_f32_16x16x32_bf16 v[32:35], v[162:165], v[214:217], v[32:35]
	v_mfma_f32_16x16x32_bf16 v[20:23], v[150:153], v[222:225], v[20:23]
	v_mfma_f32_16x16x32_bf16 v[16:19], v[162:165], v[222:225], v[16:19]
	v_mfma_f32_16x16x32_bf16 v[44:47], v[166:169], v[182:185], v[44:47]
	v_mfma_f32_16x16x32_bf16 v[40:43], v[174:177], v[182:185], v[40:43]
	v_mfma_f32_16x16x32_bf16 v[28:31], v[166:169], v[190:193], v[28:31]
	v_mfma_f32_16x16x32_bf16 v[24:27], v[174:177], v[190:193], v[24:27]
	v_mfma_f32_16x16x32_bf16 v[12:15], v[166:169], v[210:213], v[12:15]
	v_mfma_f32_16x16x32_bf16 v[8:11], v[174:177], v[210:213], v[8:11]
	v_mfma_f32_16x16x32_bf16 v[4:7], v[166:169], v[218:221], v[4:7]
	v_mfma_f32_16x16x32_bf16 v[0:3], v[174:177], v[218:221], v[0:3]
	v_mfma_f32_16x16x32_bf16 v[44:47], v[170:173], v[186:189], v[44:47]
	v_mfma_f32_16x16x32_bf16 v[40:43], v[178:181], v[186:189], v[40:43]
	v_mfma_f32_16x16x32_bf16 v[28:31], v[170:173], v[194:197], v[28:31]
	v_mfma_f32_16x16x32_bf16 v[24:27], v[178:181], v[194:197], v[24:27]
	v_mfma_f32_16x16x32_bf16 v[12:15], v[170:173], v[214:217], v[12:15]
	v_mfma_f32_16x16x32_bf16 v[8:11], v[178:181], v[214:217], v[8:11]
	v_mfma_f32_16x16x32_bf16 v[4:7], v[170:173], v[222:225], v[4:7]
	v_mfma_f32_16x16x32_bf16 v[0:3], v[178:181], v[222:225], v[0:3]
	s_barrier
	s_setprio 0
	s_add_i32 s58, 0, 0x18000
	v_add_u32_e32 v145, s58, v142
	s_add_i32 s59, 0, 0x1c000
	ds_read_b128 v[146:149], v145
	ds_read_b128 v[150:153], v145 offset:1024
	ds_read_b128 v[158:161], v145 offset:2048
	ds_read_b128 v[162:165], v145 offset:3072
	v_add_u32_e32 v145, s59, v142
	ds_read_b128 v[166:169], v145
	ds_read_b128 v[170:173], v145 offset:1024
	ds_read_b128 v[174:177], v145 offset:2048
	ds_read_b128 v[178:181], v145 offset:3072
	s_add_u32 s56, s84, 0x20000
	s_addc_u32 s57, s85, 0
	s_mov_b32 m0, s18
	v_lshl_add_u64 v[204:205], s[56:57], 0, v[134:135]
	ds_read_b128 v[182:185], v144 offset:32768
	ds_read_b128 v[186:189], v144 offset:33792
	ds_read_b128 v[190:193], v144 offset:34816
	ds_read_b128 v[194:197], v144 offset:35840
	ds_read_b128 v[210:213], v144 offset:36864
	ds_read_b128 v[214:217], v144 offset:37888
	ds_read_b128 v[218:221], v144 offset:38912
	ds_read_b128 v[222:225], v144 offset:39936
	global_load_lds_dwordx4 v[204:205], off
	v_lshl_add_u64 v[204:205], s[56:57], 0, v[132:133]
	s_mov_b32 m0, s20
	s_nop 0
	global_load_lds_dwordx4 v[204:205], off
	s_waitcnt vmcnt(8)
	s_waitcnt lgkmcnt(0)
	s_setprio 1
	s_barrier
	v_mfma_f32_16x16x32_bf16 v[126:129], v[146:149], v[182:185], v[126:129]
	v_mfma_f32_16x16x32_bf16 v[122:125], v[158:161], v[182:185], v[122:125]
	v_mfma_f32_16x16x32_bf16 v[118:121], v[146:149], v[190:193], v[118:121]
	v_mfma_f32_16x16x32_bf16 v[114:117], v[158:161], v[190:193], v[114:117]
	v_mfma_f32_16x16x32_bf16 v[102:105], v[146:149], v[210:213], v[102:105]
	v_mfma_f32_16x16x32_bf16 v[98:101], v[158:161], v[210:213], v[98:101]
	v_mfma_f32_16x16x32_bf16 v[84:87], v[146:149], v[218:221], v[84:87]
	v_mfma_f32_16x16x32_bf16 v[80:83], v[158:161], v[218:221], v[80:83]
	v_mfma_f32_16x16x32_bf16 v[126:129], v[150:153], v[186:189], v[126:129]
	v_mfma_f32_16x16x32_bf16 v[122:125], v[162:165], v[186:189], v[122:125]
	v_mfma_f32_16x16x32_bf16 v[118:121], v[150:153], v[194:197], v[118:121]
	v_mfma_f32_16x16x32_bf16 v[114:117], v[162:165], v[194:197], v[114:117]
	v_mfma_f32_16x16x32_bf16 v[102:105], v[150:153], v[214:217], v[102:105]
	v_mfma_f32_16x16x32_bf16 v[98:101], v[162:165], v[214:217], v[98:101]
	v_mfma_f32_16x16x32_bf16 v[84:87], v[150:153], v[222:225], v[84:87]
	v_mfma_f32_16x16x32_bf16 v[80:83], v[162:165], v[222:225], v[80:83]
	v_mfma_f32_16x16x32_bf16 v[110:113], v[166:169], v[182:185], v[110:113]
	v_mfma_f32_16x16x32_bf16 v[106:109], v[174:177], v[182:185], v[106:109]
	v_mfma_f32_16x16x32_bf16 v[92:95], v[166:169], v[190:193], v[92:95]
	v_mfma_f32_16x16x32_bf16 v[88:91], v[174:177], v[190:193], v[88:91]
	v_mfma_f32_16x16x32_bf16 v[76:79], v[166:169], v[210:213], v[76:79]
	v_mfma_f32_16x16x32_bf16 v[72:75], v[174:177], v[210:213], v[72:75]
	v_mfma_f32_16x16x32_bf16 v[68:71], v[166:169], v[218:221], v[68:71]
	v_mfma_f32_16x16x32_bf16 v[64:67], v[174:177], v[218:221], v[64:67]
	v_mfma_f32_16x16x32_bf16 v[110:113], v[170:173], v[186:189], v[110:113]
	v_mfma_f32_16x16x32_bf16 v[106:109], v[178:181], v[186:189], v[106:109]
	v_mfma_f32_16x16x32_bf16 v[92:95], v[170:173], v[194:197], v[92:95]
	v_mfma_f32_16x16x32_bf16 v[88:91], v[178:181], v[194:197], v[88:91]
	v_mfma_f32_16x16x32_bf16 v[76:79], v[170:173], v[214:217], v[76:79]
	v_mfma_f32_16x16x32_bf16 v[72:75], v[178:181], v[214:217], v[72:75]
	v_mfma_f32_16x16x32_bf16 v[68:71], v[170:173], v[222:225], v[68:71]
	v_mfma_f32_16x16x32_bf16 v[64:67], v[178:181], v[222:225], v[64:67]
	s_barrier
	s_setprio 0
	s_add_i32 s56, s58, s75
	v_lshl_add_u64 v[154:155], v[154:155], 0, s[64:65]
	s_mov_b32 m0, s56
	ds_read_b128 v[182:185], v144 offset:49152
	ds_read_b128 v[186:189], v144 offset:50176
	ds_read_b128 v[190:193], v144 offset:51200
	ds_read_b128 v[194:197], v144 offset:52224
	ds_read_b128 v[210:213], v144 offset:53248
	ds_read_b128 v[214:217], v144 offset:54272
	ds_read_b128 v[218:221], v144 offset:55296
	ds_read_b128 v[222:225], v144 offset:56320
	global_load_lds_dwordx4 v[154:155], off
	s_add_i32 m0, s56, 0x2000
	s_add_u32 s56, s82, 0x20080
	v_lshl_add_u64 v[154:155], v[156:157], 0, s[64:65]
	s_addc_u32 s57, s83, 0
	s_add_i32 s58, s59, s75
	global_load_lds_dwordx4 v[154:155], off
	v_lshl_add_u64 v[154:155], s[56:57], 0, v[96:97]
	s_mov_b32 m0, s58
	s_nop 0
	global_load_lds_dwordx4 v[154:155], off
	v_lshl_add_u64 v[154:155], s[56:57], 0, v[130:131]
	s_add_i32 m0, s58, 0x2000
	s_nop 0
	global_load_lds_dwordx4 v[154:155], off
	v_lshl_add_u64 v[154:155], v[198:199], 0, s[64:65]
	s_mov_b32 m0, s26
	s_nop 0
	global_load_lds_dwordx4 v[154:155], off
	v_lshl_add_u64 v[154:155], v[202:203], 0, s[64:65]
	s_mov_b32 m0, s27
	s_nop 0
	global_load_lds_dwordx4 v[154:155], off
	s_waitcnt vmcnt(8)
	s_waitcnt lgkmcnt(0)
	s_setprio 1
	s_barrier
	v_mfma_f32_16x16x32_bf16 v[60:63], v[146:149], v[182:185], v[60:63]
	v_mfma_f32_16x16x32_bf16 v[56:59], v[158:161], v[182:185], v[56:59]
	v_mfma_f32_16x16x32_bf16 v[52:55], v[146:149], v[190:193], v[52:55]
	v_mfma_f32_16x16x32_bf16 v[48:51], v[158:161], v[190:193], v[48:51]
	v_mfma_f32_16x16x32_bf16 v[36:39], v[146:149], v[210:213], v[36:39]
	v_mfma_f32_16x16x32_bf16 v[32:35], v[158:161], v[210:213], v[32:35]
	v_mfma_f32_16x16x32_bf16 v[20:23], v[146:149], v[218:221], v[20:23]
	v_mfma_f32_16x16x32_bf16 v[16:19], v[158:161], v[218:221], v[16:19]
	v_mfma_f32_16x16x32_bf16 v[60:63], v[150:153], v[186:189], v[60:63]
	v_mfma_f32_16x16x32_bf16 v[56:59], v[162:165], v[186:189], v[56:59]
	v_mfma_f32_16x16x32_bf16 v[52:55], v[150:153], v[194:197], v[52:55]
	v_mfma_f32_16x16x32_bf16 v[48:51], v[162:165], v[194:197], v[48:51]
	v_mfma_f32_16x16x32_bf16 v[36:39], v[150:153], v[214:217], v[36:39]
	v_mfma_f32_16x16x32_bf16 v[32:35], v[162:165], v[214:217], v[32:35]
	v_mfma_f32_16x16x32_bf16 v[20:23], v[150:153], v[222:225], v[20:23]
	v_mfma_f32_16x16x32_bf16 v[16:19], v[162:165], v[222:225], v[16:19]
	v_mfma_f32_16x16x32_bf16 v[44:47], v[166:169], v[182:185], v[44:47]
	v_mfma_f32_16x16x32_bf16 v[40:43], v[174:177], v[182:185], v[40:43]
	v_mfma_f32_16x16x32_bf16 v[28:31], v[166:169], v[190:193], v[28:31]
	v_mfma_f32_16x16x32_bf16 v[24:27], v[174:177], v[190:193], v[24:27]
	v_mfma_f32_16x16x32_bf16 v[12:15], v[166:169], v[210:213], v[12:15]
	v_mfma_f32_16x16x32_bf16 v[8:11], v[174:177], v[210:213], v[8:11]
	v_mfma_f32_16x16x32_bf16 v[4:7], v[166:169], v[218:221], v[4:7]
	v_mfma_f32_16x16x32_bf16 v[0:3], v[174:177], v[218:221], v[0:3]
	v_mfma_f32_16x16x32_bf16 v[44:47], v[170:173], v[186:189], v[44:47]
	v_mfma_f32_16x16x32_bf16 v[40:43], v[178:181], v[186:189], v[40:43]
	v_mfma_f32_16x16x32_bf16 v[28:31], v[170:173], v[194:197], v[28:31]
	v_mfma_f32_16x16x32_bf16 v[24:27], v[178:181], v[194:197], v[24:27]
	v_mfma_f32_16x16x32_bf16 v[12:15], v[170:173], v[214:217], v[12:15]
	v_mfma_f32_16x16x32_bf16 v[8:11], v[178:181], v[214:217], v[8:11]
	v_mfma_f32_16x16x32_bf16 v[4:7], v[170:173], v[222:225], v[4:7]
	v_mfma_f32_16x16x32_bf16 v[0:3], v[178:181], v[222:225], v[0:3]
	s_barrier
	s_setprio 0
	s_add_i32 s55, s55, 2
	s_add_u32 s68, s68, 0x100
	s_addc_u32 s69, s69, 0
	s_add_u32 s51, s51, 0x100
	s_addc_u32 s54, s54, 0
	s_cmp_gt_u32 s55, 5
	s_cbranch_scc0 .LBB0_636
	v_readlane_b32 s6, v251, 54
	v_readlane_b32 s7, v251, 55
	s_and_b64 vcc, exec, s[6:7]
	s_cbranch_vccz .LBB0_639
	s_barrier

.LBB0_656:
	s_add_u32 s58, s68, 0xfffe0080
	s_addc_u32 s59, s69, -1
	s_add_i32 s61, 0, 0x10000
	s_cmp_eq_u32 s57, 4
	s_cselect_b32 s85, s43, s59
	s_cselect_b32 s84, s51, s58
	v_add_u32_e32 v145, s61, v142
	s_cselect_b32 s83, s31, s56
	s_cselect_b32 s82, s54, s55
	s_add_i32 s62, 0, 0x14000
	ds_read_b128 v[146:149], v145
	ds_read_b128 v[150:153], v145 offset:1024
	ds_read_b128 v[158:161], v145 offset:2048
	ds_read_b128 v[162:165], v145 offset:3072
	v_add_u32_e32 v145, s62, v142
	ds_read_b128 v[166:169], v145
	ds_read_b128 v[170:173], v145 offset:1024
	ds_read_b128 v[174:177], v145 offset:2048
	ds_read_b128 v[178:181], v145 offset:3072
	v_lshl_add_u64 v[154:155], s[68:69], 0, v[136:137]
	s_add_i32 m0, s18, 0xc000
	ds_read_b128 v[182:185], v144
	ds_read_b128 v[186:189], v144 offset:1024
	ds_read_b128 v[190:193], v144 offset:2048
	ds_read_b128 v[194:197], v144 offset:3072
	ds_read_b128 v[210:213], v144 offset:4096
	ds_read_b128 v[214:217], v144 offset:5120
	ds_read_b128 v[218:221], v144 offset:6144
	ds_read_b128 v[222:225], v144 offset:7168
	global_load_lds_dwordx4 v[154:155], off
	v_lshl_add_u64 v[154:155], s[68:69], 0, v[138:139]
	s_add_i32 m0, s18, 0xe000
	s_nop 0
	global_load_lds_dwordx4 v[154:155], off
	s_waitcnt vmcnt(8)
	s_waitcnt lgkmcnt(0)
	s_setprio 1
	s_barrier
	v_mfma_f32_16x16x32_bf16 v[126:129], v[146:149], v[182:185], v[126:129]
	v_mfma_f32_16x16x32_bf16 v[122:125], v[158:161], v[182:185], v[122:125]
	v_mfma_f32_16x16x32_bf16 v[118:121], v[146:149], v[190:193], v[118:121]
	v_mfma_f32_16x16x32_bf16 v[114:117], v[158:161], v[190:193], v[114:117]
	v_mfma_f32_16x16x32_bf16 v[102:105], v[146:149], v[210:213], v[102:105]
	v_mfma_f32_16x16x32_bf16 v[98:101], v[158:161], v[210:213], v[98:101]
	v_mfma_f32_16x16x32_bf16 v[84:87], v[146:149], v[218:221], v[84:87]
	v_mfma_f32_16x16x32_bf16 v[80:83], v[158:161], v[218:221], v[80:83]
	v_mfma_f32_16x16x32_bf16 v[126:129], v[150:153], v[186:189], v[126:129]
	v_mfma_f32_16x16x32_bf16 v[122:125], v[162:165], v[186:189], v[122:125]
	v_mfma_f32_16x16x32_bf16 v[118:121], v[150:153], v[194:197], v[118:121]
	v_mfma_f32_16x16x32_bf16 v[114:117], v[162:165], v[194:197], v[114:117]
	v_mfma_f32_16x16x32_bf16 v[102:105], v[150:153], v[214:217], v[102:105]
	v_mfma_f32_16x16x32_bf16 v[98:101], v[162:165], v[214:217], v[98:101]
	v_mfma_f32_16x16x32_bf16 v[84:87], v[150:153], v[222:225], v[84:87]
	v_mfma_f32_16x16x32_bf16 v[80:83], v[162:165], v[222:225], v[80:83]
	v_mfma_f32_16x16x32_bf16 v[110:113], v[166:169], v[182:185], v[110:113]
	v_mfma_f32_16x16x32_bf16 v[106:109], v[174:177], v[182:185], v[106:109]
	v_mfma_f32_16x16x32_bf16 v[92:95], v[166:169], v[190:193], v[92:95]
	v_mfma_f32_16x16x32_bf16 v[88:91], v[174:177], v[190:193], v[88:91]
	v_mfma_f32_16x16x32_bf16 v[76:79], v[166:169], v[210:213], v[76:79]
	v_mfma_f32_16x16x32_bf16 v[72:75], v[174:177], v[210:213], v[72:75]
	v_mfma_f32_16x16x32_bf16 v[68:71], v[166:169], v[218:221], v[68:71]
	v_mfma_f32_16x16x32_bf16 v[64:67], v[174:177], v[218:221], v[64:67]
	v_mfma_f32_16x16x32_bf16 v[110:113], v[170:173], v[186:189], v[110:113]
	v_mfma_f32_16x16x32_bf16 v[106:109], v[178:181], v[186:189], v[106:109]
	v_mfma_f32_16x16x32_bf16 v[92:95], v[170:173], v[194:197], v[92:95]
	v_mfma_f32_16x16x32_bf16 v[88:91], v[178:181], v[194:197], v[88:91]
	v_mfma_f32_16x16x32_bf16 v[76:79], v[170:173], v[214:217], v[76:79]
	v_mfma_f32_16x16x32_bf16 v[72:75], v[178:181], v[214:217], v[72:75]
	v_mfma_f32_16x16x32_bf16 v[68:71], v[170:173], v[222:225], v[68:71]
	v_mfma_f32_16x16x32_bf16 v[64:67], v[178:181], v[222:225], v[64:67]
	s_barrier
	s_setprio 0
	s_add_i32 s58, s61, s75
	v_lshl_add_u64 v[154:155], s[82:83], 0, v[96:97]
	s_mov_b32 m0, s58
	ds_read_b128 v[182:185], v144 offset:16384
	ds_read_b128 v[186:189], v144 offset:17408
	ds_read_b128 v[190:193], v144 offset:18432
	ds_read_b128 v[194:197], v144 offset:19456
	ds_read_b128 v[210:213], v144 offset:20480
	ds_read_b128 v[214:217], v144 offset:21504
	ds_read_b128 v[218:221], v144 offset:22528
	ds_read_b128 v[222:225], v144 offset:23552
	global_load_lds_dwordx4 v[154:155], off
	s_add_i32 m0, s58, 0x2000
	s_add_u32 s58, s82, 0x20000
	v_lshl_add_u64 v[156:157], s[82:83], 0, v[130:131]
	s_addc_u32 s59, s83, 0
	s_add_i32 s61, s62, s75
	global_load_lds_dwordx4 v[156:157], off
	v_lshl_add_u64 v[198:199], s[58:59], 0, v[96:97]
	s_mov_b32 m0, s61
	v_lshl_add_u64 v[202:203], s[84:85], 0, v[132:133]
	global_load_lds_dwordx4 v[198:199], off
	v_lshl_add_u64 v[198:199], s[58:59], 0, v[130:131]
	s_add_i32 m0, s61, 0x2000
	s_nop 0
	global_load_lds_dwordx4 v[198:199], off
	v_lshl_add_u64 v[198:199], s[84:85], 0, v[134:135]
	s_mov_b32 m0, s18
	s_nop 0
	global_load_lds_dwordx4 v[198:199], off
	s_mov_b32 m0, s20
	s_nop 0
	global_load_lds_dwordx4 v[202:203], off
	s_waitcnt vmcnt(8)
	s_waitcnt lgkmcnt(0)
	s_setprio 1
	s_barrier
	v_mfma_f32_16x16x32_bf16 v[60:63], v[146:149], v[182:185], v[60:63]
	v_mfma_f32_16x16x32_bf16 v[56:59], v[158:161], v[182:185], v[56:59]
	v_mfma_f32_16x16x32_bf16 v[52:55], v[146:149], v[190:193], v[52:55]
	v_mfma_f32_16x16x32_bf16 v[48:51], v[158:161], v[190:193], v[48:51]
	v_mfma_f32_16x16x32_bf16 v[36:39], v[146:149], v[210:213], v[36:39]
	v_mfma_f32_16x16x32_bf16 v[32:35], v[158:161], v[210:213], v[32:35]
	v_mfma_f32_16x16x32_bf16 v[20:23], v[146:149], v[218:221], v[20:23]
	v_mfma_f32_16x16x32_bf16 v[16:19], v[158:161], v[218:221], v[16:19]
	v_mfma_f32_16x16x32_bf16 v[60:63], v[150:153], v[186:189], v[60:63]
	v_mfma_f32_16x16x32_bf16 v[56:59], v[162:165], v[186:189], v[56:59]
	v_mfma_f32_16x16x32_bf16 v[52:55], v[150:153], v[194:197], v[52:55]
	v_mfma_f32_16x16x32_bf16 v[48:51], v[162:165], v[194:197], v[48:51]
	v_mfma_f32_16x16x32_bf16 v[36:39], v[150:153], v[214:217], v[36:39]
	v_mfma_f32_16x16x32_bf16 v[32:35], v[162:165], v[214:217], v[32:35]
	v_mfma_f32_16x16x32_bf16 v[20:23], v[150:153], v[222:225], v[20:23]
	v_mfma_f32_16x16x32_bf16 v[16:19], v[162:165], v[222:225], v[16:19]
	v_mfma_f32_16x16x32_bf16 v[44:47], v[166:169], v[182:185], v[44:47]
	v_mfma_f32_16x16x32_bf16 v[40:43], v[174:177], v[182:185], v[40:43]
	v_mfma_f32_16x16x32_bf16 v[28:31], v[166:169], v[190:193], v[28:31]
	v_mfma_f32_16x16x32_bf16 v[24:27], v[174:177], v[190:193], v[24:27]
	v_mfma_f32_16x16x32_bf16 v[12:15], v[166:169], v[210:213], v[12:15]
	v_mfma_f32_16x16x32_bf16 v[8:11], v[174:177], v[210:213], v[8:11]
	v_mfma_f32_16x16x32_bf16 v[4:7], v[166:169], v[218:221], v[4:7]
	v_mfma_f32_16x16x32_bf16 v[0:3], v[174:177], v[218:221], v[0:3]
	v_mfma_f32_16x16x32_bf16 v[44:47], v[170:173], v[186:189], v[44:47]
	v_mfma_f32_16x16x32_bf16 v[40:43], v[178:181], v[186:189], v[40:43]
	v_mfma_f32_16x16x32_bf16 v[28:31], v[170:173], v[194:197], v[28:31]
	v_mfma_f32_16x16x32_bf16 v[24:27], v[178:181], v[194:197], v[24:27]
	v_mfma_f32_16x16x32_bf16 v[12:15], v[170:173], v[214:217], v[12:15]
	v_mfma_f32_16x16x32_bf16 v[8:11], v[178:181], v[214:217], v[8:11]
	v_mfma_f32_16x16x32_bf16 v[4:7], v[170:173], v[222:225], v[4:7]
	v_mfma_f32_16x16x32_bf16 v[0:3], v[178:181], v[222:225], v[0:3]
	s_barrier
	s_setprio 0
	s_add_i32 s61, 0, 0x18000
	v_add_u32_e32 v145, s61, v142
	s_add_i32 s62, 0, 0x1c000
	ds_read_b128 v[146:149], v145
	ds_read_b128 v[150:153], v145 offset:1024
	ds_read_b128 v[158:161], v145 offset:2048
	ds_read_b128 v[162:165], v145 offset:3072
	v_add_u32_e32 v145, s62, v142
	ds_read_b128 v[166:169], v145
	ds_read_b128 v[170:173], v145 offset:1024
	ds_read_b128 v[174:177], v145 offset:2048
	ds_read_b128 v[178:181], v145 offset:3072
	s_add_u32 s58, s84, 0x20000
	s_addc_u32 s59, s85, 0
	s_mov_b32 m0, s26
	v_lshl_add_u64 v[204:205], s[58:59], 0, v[134:135]
	ds_read_b128 v[182:185], v144 offset:32768
	ds_read_b128 v[186:189], v144 offset:33792
	ds_read_b128 v[190:193], v144 offset:34816
	ds_read_b128 v[194:197], v144 offset:35840
	ds_read_b128 v[210:213], v144 offset:36864
	ds_read_b128 v[214:217], v144 offset:37888
	ds_read_b128 v[218:221], v144 offset:38912
	ds_read_b128 v[222:225], v144 offset:39936
	global_load_lds_dwordx4 v[204:205], off
	v_lshl_add_u64 v[204:205], s[58:59], 0, v[132:133]
	s_mov_b32 m0, s27
	s_nop 0
	global_load_lds_dwordx4 v[204:205], off
	s_waitcnt vmcnt(8)
	s_waitcnt lgkmcnt(0)
	s_setprio 1
	s_barrier
	v_mfma_f32_16x16x32_bf16 v[126:129], v[146:149], v[182:185], v[126:129]
	v_mfma_f32_16x16x32_bf16 v[122:125], v[158:161], v[182:185], v[122:125]
	v_mfma_f32_16x16x32_bf16 v[118:121], v[146:149], v[190:193], v[118:121]
	v_mfma_f32_16x16x32_bf16 v[114:117], v[158:161], v[190:193], v[114:117]
	v_mfma_f32_16x16x32_bf16 v[102:105], v[146:149], v[210:213], v[102:105]
	v_mfma_f32_16x16x32_bf16 v[98:101], v[158:161], v[210:213], v[98:101]
	v_mfma_f32_16x16x32_bf16 v[84:87], v[146:149], v[218:221], v[84:87]
	v_mfma_f32_16x16x32_bf16 v[80:83], v[158:161], v[218:221], v[80:83]
	v_mfma_f32_16x16x32_bf16 v[126:129], v[150:153], v[186:189], v[126:129]
	v_mfma_f32_16x16x32_bf16 v[122:125], v[162:165], v[186:189], v[122:125]
	v_mfma_f32_16x16x32_bf16 v[118:121], v[150:153], v[194:197], v[118:121]
	v_mfma_f32_16x16x32_bf16 v[114:117], v[162:165], v[194:197], v[114:117]
	v_mfma_f32_16x16x32_bf16 v[102:105], v[150:153], v[214:217], v[102:105]
	v_mfma_f32_16x16x32_bf16 v[98:101], v[162:165], v[214:217], v[98:101]
	v_mfma_f32_16x16x32_bf16 v[84:87], v[150:153], v[222:225], v[84:87]
	v_mfma_f32_16x16x32_bf16 v[80:83], v[162:165], v[222:225], v[80:83]
	v_mfma_f32_16x16x32_bf16 v[110:113], v[166:169], v[182:185], v[110:113]
	v_mfma_f32_16x16x32_bf16 v[106:109], v[174:177], v[182:185], v[106:109]
	v_mfma_f32_16x16x32_bf16 v[92:95], v[166:169], v[190:193], v[92:95]
	v_mfma_f32_16x16x32_bf16 v[88:91], v[174:177], v[190:193], v[88:91]
	v_mfma_f32_16x16x32_bf16 v[76:79], v[166:169], v[210:213], v[76:79]
	v_mfma_f32_16x16x32_bf16 v[72:75], v[174:177], v[210:213], v[72:75]
	v_mfma_f32_16x16x32_bf16 v[68:71], v[166:169], v[218:221], v[68:71]
	v_mfma_f32_16x16x32_bf16 v[64:67], v[174:177], v[218:221], v[64:67]
	v_mfma_f32_16x16x32_bf16 v[110:113], v[170:173], v[186:189], v[110:113]
	v_mfma_f32_16x16x32_bf16 v[106:109], v[178:181], v[186:189], v[106:109]
	v_mfma_f32_16x16x32_bf16 v[92:95], v[170:173], v[194:197], v[92:95]
	v_mfma_f32_16x16x32_bf16 v[88:91], v[178:181], v[194:197], v[88:91]
	v_mfma_f32_16x16x32_bf16 v[76:79], v[170:173], v[214:217], v[76:79]
	v_mfma_f32_16x16x32_bf16 v[72:75], v[178:181], v[214:217], v[72:75]
	v_mfma_f32_16x16x32_bf16 v[68:71], v[170:173], v[222:225], v[68:71]
	v_mfma_f32_16x16x32_bf16 v[64:67], v[178:181], v[222:225], v[64:67]
	s_barrier
	s_setprio 0
	s_add_i32 s58, s61, s75
	v_lshl_add_u64 v[154:155], v[154:155], 0, s[64:65]
	s_mov_b32 m0, s58
	ds_read_b128 v[182:185], v144 offset:49152
	ds_read_b128 v[186:189], v144 offset:50176
	ds_read_b128 v[190:193], v144 offset:51200
	ds_read_b128 v[194:197], v144 offset:52224
	ds_read_b128 v[210:213], v144 offset:53248
	ds_read_b128 v[214:217], v144 offset:54272
	ds_read_b128 v[218:221], v144 offset:55296
	ds_read_b128 v[222:225], v144 offset:56320
	global_load_lds_dwordx4 v[154:155], off
	s_add_i32 m0, s58, 0x2000
	s_add_u32 s58, s82, 0x20080
	v_lshl_add_u64 v[154:155], v[156:157], 0, s[64:65]
	s_addc_u32 s59, s83, 0
	s_add_i32 s61, s62, s75
	global_load_lds_dwordx4 v[154:155], off
	v_lshl_add_u64 v[154:155], s[58:59], 0, v[96:97]
	s_mov_b32 m0, s61
	s_nop 0
	global_load_lds_dwordx4 v[154:155], off
	v_lshl_add_u64 v[154:155], s[58:59], 0, v[130:131]
	s_add_i32 m0, s61, 0x2000
	s_nop 0
	global_load_lds_dwordx4 v[154:155], off
	v_lshl_add_u64 v[154:155], v[198:199], 0, s[64:65]
	s_mov_b32 m0, s28
	s_nop 0
	global_load_lds_dwordx4 v[154:155], off
	v_lshl_add_u64 v[154:155], v[202:203], 0, s[64:65]
	s_mov_b32 m0, s33
	s_nop 0
	global_load_lds_dwordx4 v[154:155], off
	s_waitcnt vmcnt(8)
	s_waitcnt lgkmcnt(0)
	s_setprio 1
	s_barrier
	v_mfma_f32_16x16x32_bf16 v[60:63], v[146:149], v[182:185], v[60:63]
	v_mfma_f32_16x16x32_bf16 v[56:59], v[158:161], v[182:185], v[56:59]
	v_mfma_f32_16x16x32_bf16 v[52:55], v[146:149], v[190:193], v[52:55]
	v_mfma_f32_16x16x32_bf16 v[48:51], v[158:161], v[190:193], v[48:51]
	v_mfma_f32_16x16x32_bf16 v[36:39], v[146:149], v[210:213], v[36:39]
	v_mfma_f32_16x16x32_bf16 v[32:35], v[158:161], v[210:213], v[32:35]
	v_mfma_f32_16x16x32_bf16 v[20:23], v[146:149], v[218:221], v[20:23]
	v_mfma_f32_16x16x32_bf16 v[16:19], v[158:161], v[218:221], v[16:19]
	v_mfma_f32_16x16x32_bf16 v[60:63], v[150:153], v[186:189], v[60:63]
	v_mfma_f32_16x16x32_bf16 v[56:59], v[162:165], v[186:189], v[56:59]
	v_mfma_f32_16x16x32_bf16 v[52:55], v[150:153], v[194:197], v[52:55]
	v_mfma_f32_16x16x32_bf16 v[48:51], v[162:165], v[194:197], v[48:51]
	v_mfma_f32_16x16x32_bf16 v[36:39], v[150:153], v[214:217], v[36:39]
	v_mfma_f32_16x16x32_bf16 v[32:35], v[162:165], v[214:217], v[32:35]
	v_mfma_f32_16x16x32_bf16 v[20:23], v[150:153], v[222:225], v[20:23]
	v_mfma_f32_16x16x32_bf16 v[16:19], v[162:165], v[222:225], v[16:19]
	v_mfma_f32_16x16x32_bf16 v[44:47], v[166:169], v[182:185], v[44:47]
	v_mfma_f32_16x16x32_bf16 v[40:43], v[174:177], v[182:185], v[40:43]
	v_mfma_f32_16x16x32_bf16 v[28:31], v[166:169], v[190:193], v[28:31]
	v_mfma_f32_16x16x32_bf16 v[24:27], v[174:177], v[190:193], v[24:27]
	v_mfma_f32_16x16x32_bf16 v[12:15], v[166:169], v[210:213], v[12:15]
	v_mfma_f32_16x16x32_bf16 v[8:11], v[174:177], v[210:213], v[8:11]
	v_mfma_f32_16x16x32_bf16 v[4:7], v[166:169], v[218:221], v[4:7]
	v_mfma_f32_16x16x32_bf16 v[0:3], v[174:177], v[218:221], v[0:3]
	v_mfma_f32_16x16x32_bf16 v[44:47], v[170:173], v[186:189], v[44:47]
	v_mfma_f32_16x16x32_bf16 v[40:43], v[178:181], v[186:189], v[40:43]
	v_mfma_f32_16x16x32_bf16 v[28:31], v[170:173], v[194:197], v[28:31]
	v_mfma_f32_16x16x32_bf16 v[24:27], v[178:181], v[194:197], v[24:27]
	v_mfma_f32_16x16x32_bf16 v[12:15], v[170:173], v[214:217], v[12:15]
	v_mfma_f32_16x16x32_bf16 v[8:11], v[178:181], v[214:217], v[8:11]
	v_mfma_f32_16x16x32_bf16 v[4:7], v[170:173], v[222:225], v[4:7]
	v_mfma_f32_16x16x32_bf16 v[0:3], v[178:181], v[222:225], v[0:3]
	s_barrier
	s_setprio 0
	s_add_i32 s57, s57, 2
	s_add_u32 s68, s68, 0x100
	s_addc_u32 s69, s69, 0
	s_add_u32 s55, s55, 0x100
	s_addc_u32 s56, s56, 0
	s_cmp_gt_u32 s57, 5
	s_cbranch_scc0 .LBB0_656
	v_readlane_b32 s6, v251, 54
	v_readlane_b32 s7, v251, 55
	s_and_b64 vcc, exec, s[6:7]
	s_cbranch_vccz .LBB0_659
	s_barrier

.LBB0_1038:
	s_add_u32 s34, s44, 0xfff80080
	s_addc_u32 s35, s45, -1
	s_add_i32 s38, 0, 0x10000
	s_cmp_eq_u32 s33, 28
	s_cselect_b32 s87, s10, s35
	s_cselect_b32 s86, s12, s34
	s_cselect_b32 s85, s18, s31
	s_cselect_b32 s84, s20, s28
	s_add_i32 s39, 0, 0x14000
	v_add_u32_e32 v156, s38, v169
	v_add_u32_e32 v164, s39, v169
	ds_read_b128 v[130:133], v156
	ds_read_b128 v[134:137], v156 offset:1024
	ds_read_b128 v[152:155], v156 offset:2048
	ds_read_b128 v[156:159], v156 offset:3072
	ds_read_b128 v[160:163], v164
	ds_read_b128 v[172:175], v164 offset:1024
	ds_read_b128 v[176:179], v164 offset:2048
	ds_read_b128 v[180:183], v164 offset:3072
	v_lshl_add_u64 v[164:165], s[44:45], 0, v[148:149]
	s_add_i32 m0, s58, 0xc000
	ds_read_b128 v[184:187], v171
	ds_read_b128 v[188:191], v171 offset:1024
	ds_read_b128 v[192:195], v171 offset:2048
	ds_read_b128 v[196:199], v171 offset:3072
	ds_read_b128 v[202:205], v171 offset:4096
	ds_read_b128 v[210:213], v171 offset:5120
	ds_read_b128 v[214:217], v171 offset:6144
	ds_read_b128 v[218:221], v171 offset:7168
	global_load_lds_dwordx4 v[164:165], off
	v_lshl_add_u64 v[164:165], s[44:45], 0, v[150:151]
	s_add_i32 m0, s58, 0xe000
	s_nop 0
	global_load_lds_dwordx4 v[164:165], off
	s_waitcnt vmcnt(8)
	s_waitcnt lgkmcnt(0)
	s_setprio 1
	s_barrier
	v_mfma_f32_16x16x32_bf16 v[126:129], v[130:133], v[184:187], v[126:129]
	v_mfma_f32_16x16x32_bf16 v[122:125], v[152:155], v[184:187], v[122:125]
	v_mfma_f32_16x16x32_bf16 v[110:113], v[130:133], v[192:195], v[110:113]
	v_mfma_f32_16x16x32_bf16 v[106:109], v[152:155], v[192:195], v[106:109]
	v_mfma_f32_16x16x32_bf16 v[92:95], v[130:133], v[202:205], v[92:95]
	v_mfma_f32_16x16x32_bf16 v[88:91], v[152:155], v[202:205], v[88:91]
	v_mfma_f32_16x16x32_bf16 v[76:79], v[130:133], v[214:217], v[76:79]
	v_mfma_f32_16x16x32_bf16 v[72:75], v[152:155], v[214:217], v[72:75]
	v_mfma_f32_16x16x32_bf16 v[126:129], v[134:137], v[188:191], v[126:129]
	v_mfma_f32_16x16x32_bf16 v[122:125], v[156:159], v[188:191], v[122:125]
	v_mfma_f32_16x16x32_bf16 v[110:113], v[134:137], v[196:199], v[110:113]
	v_mfma_f32_16x16x32_bf16 v[106:109], v[156:159], v[196:199], v[106:109]
	v_mfma_f32_16x16x32_bf16 v[92:95], v[134:137], v[210:213], v[92:95]
	v_mfma_f32_16x16x32_bf16 v[88:91], v[156:159], v[210:213], v[88:91]
	v_mfma_f32_16x16x32_bf16 v[76:79], v[134:137], v[218:221], v[76:79]
	v_mfma_f32_16x16x32_bf16 v[72:75], v[156:159], v[218:221], v[72:75]
	v_mfma_f32_16x16x32_bf16 v[118:121], v[160:163], v[184:187], v[118:121]
	v_mfma_f32_16x16x32_bf16 v[114:117], v[176:179], v[184:187], v[114:117]
	v_mfma_f32_16x16x32_bf16 v[102:105], v[160:163], v[192:195], v[102:105]
	v_mfma_f32_16x16x32_bf16 v[98:101], v[176:179], v[192:195], v[98:101]
	v_mfma_f32_16x16x32_bf16 v[84:87], v[160:163], v[202:205], v[84:87]
	v_mfma_f32_16x16x32_bf16 v[80:83], v[176:179], v[202:205], v[80:83]
	v_mfma_f32_16x16x32_bf16 v[68:71], v[160:163], v[214:217], v[68:71]
	v_mfma_f32_16x16x32_bf16 v[64:67], v[176:179], v[214:217], v[64:67]
	v_mfma_f32_16x16x32_bf16 v[118:121], v[172:175], v[188:191], v[118:121]
	v_mfma_f32_16x16x32_bf16 v[114:117], v[180:183], v[188:191], v[114:117]
	v_mfma_f32_16x16x32_bf16 v[102:105], v[172:175], v[196:199], v[102:105]
	v_mfma_f32_16x16x32_bf16 v[98:101], v[180:183], v[196:199], v[98:101]
	v_mfma_f32_16x16x32_bf16 v[84:87], v[172:175], v[210:213], v[84:87]
	v_mfma_f32_16x16x32_bf16 v[80:83], v[180:183], v[210:213], v[80:83]
	v_mfma_f32_16x16x32_bf16 v[68:71], v[172:175], v[218:221], v[68:71]
	v_mfma_f32_16x16x32_bf16 v[64:67], v[180:183], v[218:221], v[64:67]
	s_barrier
	s_setprio 0
	s_add_i32 s34, s38, s75
	v_lshl_add_u64 v[164:165], s[84:85], 0, v[96:97]
	s_mov_b32 m0, s34
	ds_read_b128 v[184:187], v171 offset:16384
	ds_read_b128 v[188:191], v171 offset:17408
	ds_read_b128 v[192:195], v171 offset:18432
	ds_read_b128 v[196:199], v171 offset:19456
	ds_read_b128 v[202:205], v171 offset:20480
	ds_read_b128 v[210:213], v171 offset:21504
	ds_read_b128 v[214:217], v171 offset:22528
	ds_read_b128 v[218:221], v171 offset:23552
	global_load_lds_dwordx4 v[164:165], off
	s_add_i32 m0, s34, 0x2000
	s_add_u32 s34, s84, 0x80000
	v_lshl_add_u64 v[222:223], s[84:85], 0, v[142:143]
	s_addc_u32 s35, s85, 0
	s_add_i32 s38, s39, s75
	global_load_lds_dwordx4 v[222:223], off
	v_lshl_add_u64 v[224:225], s[34:35], 0, v[96:97]
	s_mov_b32 m0, s38
	v_lshl_add_u64 v[226:227], s[86:87], 0, v[144:145]
	global_load_lds_dwordx4 v[224:225], off
	v_lshl_add_u64 v[224:225], s[34:35], 0, v[142:143]
	s_add_i32 m0, s38, 0x2000
	s_nop 0
	global_load_lds_dwordx4 v[224:225], off
	v_lshl_add_u64 v[224:225], s[86:87], 0, v[146:147]
	s_mov_b32 m0, s58
	s_nop 0
	global_load_lds_dwordx4 v[224:225], off
	s_mov_b32 m0, s59
	s_nop 0
	global_load_lds_dwordx4 v[226:227], off
	s_waitcnt vmcnt(8)
	s_waitcnt lgkmcnt(0)
	s_setprio 1
	s_barrier
	v_mfma_f32_16x16x32_bf16 v[60:63], v[130:133], v[184:187], v[60:63]
	v_mfma_f32_16x16x32_bf16 v[56:59], v[152:155], v[184:187], v[56:59]
	v_mfma_f32_16x16x32_bf16 v[44:47], v[130:133], v[192:195], v[44:47]
	v_mfma_f32_16x16x32_bf16 v[40:43], v[152:155], v[192:195], v[40:43]
	v_mfma_f32_16x16x32_bf16 v[28:31], v[130:133], v[202:205], v[28:31]
	v_mfma_f32_16x16x32_bf16 v[24:27], v[152:155], v[202:205], v[24:27]
	v_mfma_f32_16x16x32_bf16 v[12:15], v[130:133], v[214:217], v[12:15]
	v_mfma_f32_16x16x32_bf16 v[8:11], v[152:155], v[214:217], v[8:11]
	v_mfma_f32_16x16x32_bf16 v[60:63], v[134:137], v[188:191], v[60:63]
	v_mfma_f32_16x16x32_bf16 v[56:59], v[156:159], v[188:191], v[56:59]
	v_mfma_f32_16x16x32_bf16 v[44:47], v[134:137], v[196:199], v[44:47]
	v_mfma_f32_16x16x32_bf16 v[40:43], v[156:159], v[196:199], v[40:43]
	v_mfma_f32_16x16x32_bf16 v[28:31], v[134:137], v[210:213], v[28:31]
	v_mfma_f32_16x16x32_bf16 v[24:27], v[156:159], v[210:213], v[24:27]
	v_mfma_f32_16x16x32_bf16 v[12:15], v[134:137], v[218:221], v[12:15]
	v_mfma_f32_16x16x32_bf16 v[8:11], v[156:159], v[218:221], v[8:11]
	v_mfma_f32_16x16x32_bf16 v[52:55], v[160:163], v[184:187], v[52:55]
	v_mfma_f32_16x16x32_bf16 v[48:51], v[176:179], v[184:187], v[48:51]
	v_mfma_f32_16x16x32_bf16 v[36:39], v[160:163], v[192:195], v[36:39]
	v_mfma_f32_16x16x32_bf16 v[32:35], v[176:179], v[192:195], v[32:35]
	v_mfma_f32_16x16x32_bf16 v[20:23], v[160:163], v[202:205], v[20:23]
	v_mfma_f32_16x16x32_bf16 v[16:19], v[176:179], v[202:205], v[16:19]
	v_mfma_f32_16x16x32_bf16 v[4:7], v[160:163], v[214:217], v[4:7]
	v_mfma_f32_16x16x32_bf16 v[0:3], v[176:179], v[214:217], v[0:3]
	v_mfma_f32_16x16x32_bf16 v[52:55], v[172:175], v[188:191], v[52:55]
	v_mfma_f32_16x16x32_bf16 v[48:51], v[180:183], v[188:191], v[48:51]
	v_mfma_f32_16x16x32_bf16 v[36:39], v[172:175], v[196:199], v[36:39]
	v_mfma_f32_16x16x32_bf16 v[32:35], v[180:183], v[196:199], v[32:35]
	v_mfma_f32_16x16x32_bf16 v[20:23], v[172:175], v[210:213], v[20:23]
	v_mfma_f32_16x16x32_bf16 v[16:19], v[180:183], v[210:213], v[16:19]
	v_mfma_f32_16x16x32_bf16 v[4:7], v[172:175], v[218:221], v[4:7]
	v_mfma_f32_16x16x32_bf16 v[0:3], v[180:183], v[218:221], v[0:3]
	s_barrier
	s_setprio 0
	s_add_i32 s38, 0, 0x18000
	s_add_i32 s39, 0, 0x1c000
	v_add_u32_e32 v156, s38, v169
	v_add_u32_e32 v180, s39, v169
	ds_read_b128 v[130:133], v156
	ds_read_b128 v[134:137], v156 offset:1024
	ds_read_b128 v[152:155], v156 offset:2048
	ds_read_b128 v[156:159], v156 offset:3072
	ds_read_b128 v[160:163], v180
	ds_read_b128 v[172:175], v180 offset:1024
	ds_read_b128 v[176:179], v180 offset:2048
	ds_read_b128 v[180:183], v180 offset:3072
	s_add_u32 s34, s86, 0x80000
	s_addc_u32 s35, s87, 0
	s_mov_b32 m0, s79
	v_lshl_add_u64 v[228:229], s[34:35], 0, v[146:147]
	ds_read_b128 v[184:187], v171 offset:32768
	ds_read_b128 v[188:191], v171 offset:33792
	ds_read_b128 v[192:195], v171 offset:34816
	ds_read_b128 v[196:199], v171 offset:35840
	ds_read_b128 v[202:205], v171 offset:36864
	ds_read_b128 v[210:213], v171 offset:37888
	ds_read_b128 v[214:217], v171 offset:38912
	ds_read_b128 v[218:221], v171 offset:39936
	global_load_lds_dwordx4 v[228:229], off
	v_lshl_add_u64 v[228:229], s[34:35], 0, v[144:145]
	s_mov_b32 m0, s90
	s_nop 0
	global_load_lds_dwordx4 v[228:229], off
	s_waitcnt vmcnt(8)
	s_waitcnt lgkmcnt(0)
	s_setprio 1
	s_barrier
	v_mfma_f32_16x16x32_bf16 v[126:129], v[130:133], v[184:187], v[126:129]
	v_mfma_f32_16x16x32_bf16 v[122:125], v[152:155], v[184:187], v[122:125]
	v_mfma_f32_16x16x32_bf16 v[110:113], v[130:133], v[192:195], v[110:113]
	v_mfma_f32_16x16x32_bf16 v[106:109], v[152:155], v[192:195], v[106:109]
	v_mfma_f32_16x16x32_bf16 v[92:95], v[130:133], v[202:205], v[92:95]
	v_mfma_f32_16x16x32_bf16 v[88:91], v[152:155], v[202:205], v[88:91]
	v_mfma_f32_16x16x32_bf16 v[76:79], v[130:133], v[214:217], v[76:79]
	v_mfma_f32_16x16x32_bf16 v[72:75], v[152:155], v[214:217], v[72:75]
	v_mfma_f32_16x16x32_bf16 v[126:129], v[134:137], v[188:191], v[126:129]
	v_mfma_f32_16x16x32_bf16 v[122:125], v[156:159], v[188:191], v[122:125]
	v_mfma_f32_16x16x32_bf16 v[110:113], v[134:137], v[196:199], v[110:113]
	v_mfma_f32_16x16x32_bf16 v[106:109], v[156:159], v[196:199], v[106:109]
	v_mfma_f32_16x16x32_bf16 v[92:95], v[134:137], v[210:213], v[92:95]
	v_mfma_f32_16x16x32_bf16 v[88:91], v[156:159], v[210:213], v[88:91]
	v_mfma_f32_16x16x32_bf16 v[76:79], v[134:137], v[218:221], v[76:79]
	v_mfma_f32_16x16x32_bf16 v[72:75], v[156:159], v[218:221], v[72:75]
	v_mfma_f32_16x16x32_bf16 v[118:121], v[160:163], v[184:187], v[118:121]
	v_mfma_f32_16x16x32_bf16 v[114:117], v[176:179], v[184:187], v[114:117]
	v_mfma_f32_16x16x32_bf16 v[102:105], v[160:163], v[192:195], v[102:105]
	v_mfma_f32_16x16x32_bf16 v[98:101], v[176:179], v[192:195], v[98:101]
	v_mfma_f32_16x16x32_bf16 v[84:87], v[160:163], v[202:205], v[84:87]
	v_mfma_f32_16x16x32_bf16 v[80:83], v[176:179], v[202:205], v[80:83]
	v_mfma_f32_16x16x32_bf16 v[68:71], v[160:163], v[214:217], v[68:71]
	v_mfma_f32_16x16x32_bf16 v[64:67], v[176:179], v[214:217], v[64:67]
	v_mfma_f32_16x16x32_bf16 v[118:121], v[172:175], v[188:191], v[118:121]
	v_mfma_f32_16x16x32_bf16 v[114:117], v[180:183], v[188:191], v[114:117]
	v_mfma_f32_16x16x32_bf16 v[102:105], v[172:175], v[196:199], v[102:105]
	v_mfma_f32_16x16x32_bf16 v[98:101], v[180:183], v[196:199], v[98:101]
	v_mfma_f32_16x16x32_bf16 v[84:87], v[172:175], v[210:213], v[84:87]
	v_mfma_f32_16x16x32_bf16 v[80:83], v[180:183], v[210:213], v[80:83]
	v_mfma_f32_16x16x32_bf16 v[68:71], v[172:175], v[218:221], v[68:71]
	v_mfma_f32_16x16x32_bf16 v[64:67], v[180:183], v[218:221], v[64:67]
	s_barrier
	s_setprio 0
	s_add_i32 s34, s38, s75
	v_lshl_add_u64 v[164:165], v[164:165], 0, s[64:65]
	s_mov_b32 m0, s34
	ds_read_b128 v[184:187], v171 offset:49152
	ds_read_b128 v[188:191], v171 offset:50176
	ds_read_b128 v[192:195], v171 offset:51200
	ds_read_b128 v[196:199], v171 offset:52224
	ds_read_b128 v[202:205], v171 offset:53248
	ds_read_b128 v[210:213], v171 offset:54272
	ds_read_b128 v[214:217], v171 offset:55296
	ds_read_b128 v[218:221], v171 offset:56320
	global_load_lds_dwordx4 v[164:165], off
	s_add_i32 m0, s34, 0x2000
	s_add_u32 s34, s84, 0x80080
	v_lshl_add_u64 v[164:165], v[222:223], 0, s[64:65]
	s_addc_u32 s35, s85, 0
	s_add_i32 s38, s39, s75
	global_load_lds_dwordx4 v[164:165], off
	v_lshl_add_u64 v[164:165], s[34:35], 0, v[96:97]
	s_mov_b32 m0, s38
	s_nop 0
	global_load_lds_dwordx4 v[164:165], off
	v_lshl_add_u64 v[164:165], s[34:35], 0, v[142:143]
	s_add_i32 m0, s38, 0x2000
	s_nop 0
	global_load_lds_dwordx4 v[164:165], off
	v_lshl_add_u64 v[164:165], v[224:225], 0, s[64:65]
	s_mov_b32 m0, s94
	s_nop 0
	global_load_lds_dwordx4 v[164:165], off
	v_lshl_add_u64 v[164:165], v[226:227], 0, s[64:65]
	s_mov_b32 m0, s95
	s_nop 0
	global_load_lds_dwordx4 v[164:165], off
	s_waitcnt vmcnt(8)
	s_waitcnt lgkmcnt(0)
	s_setprio 1
	s_barrier
	v_mfma_f32_16x16x32_bf16 v[60:63], v[130:133], v[184:187], v[60:63]
	v_mfma_f32_16x16x32_bf16 v[56:59], v[152:155], v[184:187], v[56:59]
	v_mfma_f32_16x16x32_bf16 v[44:47], v[130:133], v[192:195], v[44:47]
	v_mfma_f32_16x16x32_bf16 v[40:43], v[152:155], v[192:195], v[40:43]
	v_mfma_f32_16x16x32_bf16 v[28:31], v[130:133], v[202:205], v[28:31]
	v_mfma_f32_16x16x32_bf16 v[24:27], v[152:155], v[202:205], v[24:27]
	v_mfma_f32_16x16x32_bf16 v[12:15], v[130:133], v[214:217], v[12:15]
	v_mfma_f32_16x16x32_bf16 v[8:11], v[152:155], v[214:217], v[8:11]
	v_mfma_f32_16x16x32_bf16 v[60:63], v[134:137], v[188:191], v[60:63]
	v_mfma_f32_16x16x32_bf16 v[56:59], v[156:159], v[188:191], v[56:59]
	v_mfma_f32_16x16x32_bf16 v[44:47], v[134:137], v[196:199], v[44:47]
	v_mfma_f32_16x16x32_bf16 v[40:43], v[156:159], v[196:199], v[40:43]
	v_mfma_f32_16x16x32_bf16 v[28:31], v[134:137], v[210:213], v[28:31]
	v_mfma_f32_16x16x32_bf16 v[24:27], v[156:159], v[210:213], v[24:27]
	v_mfma_f32_16x16x32_bf16 v[12:15], v[134:137], v[218:221], v[12:15]
	v_mfma_f32_16x16x32_bf16 v[8:11], v[156:159], v[218:221], v[8:11]
	v_mfma_f32_16x16x32_bf16 v[52:55], v[160:163], v[184:187], v[52:55]
	v_mfma_f32_16x16x32_bf16 v[48:51], v[176:179], v[184:187], v[48:51]
	v_mfma_f32_16x16x32_bf16 v[36:39], v[160:163], v[192:195], v[36:39]
	v_mfma_f32_16x16x32_bf16 v[32:35], v[176:179], v[192:195], v[32:35]
	v_mfma_f32_16x16x32_bf16 v[20:23], v[160:163], v[202:205], v[20:23]
	v_mfma_f32_16x16x32_bf16 v[16:19], v[176:179], v[202:205], v[16:19]
	v_mfma_f32_16x16x32_bf16 v[4:7], v[160:163], v[214:217], v[4:7]
	v_mfma_f32_16x16x32_bf16 v[0:3], v[176:179], v[214:217], v[0:3]
	v_mfma_f32_16x16x32_bf16 v[52:55], v[172:175], v[188:191], v[52:55]
	v_mfma_f32_16x16x32_bf16 v[48:51], v[180:183], v[188:191], v[48:51]
	v_mfma_f32_16x16x32_bf16 v[36:39], v[172:175], v[196:199], v[36:39]
	v_mfma_f32_16x16x32_bf16 v[32:35], v[180:183], v[196:199], v[32:35]
	v_mfma_f32_16x16x32_bf16 v[20:23], v[172:175], v[210:213], v[20:23]
	v_mfma_f32_16x16x32_bf16 v[16:19], v[180:183], v[210:213], v[16:19]
	v_mfma_f32_16x16x32_bf16 v[4:7], v[172:175], v[218:221], v[4:7]
	v_mfma_f32_16x16x32_bf16 v[0:3], v[180:183], v[218:221], v[0:3]
	s_barrier
	s_setprio 0
	s_add_i32 s33, s33, 2
	s_add_u32 s44, s44, 0x100
	s_addc_u32 s45, s45, 0
	s_add_u32 s28, s28, 0x100
	s_addc_u32 s31, s31, 0
	s_cmp_gt_u32 s33, 29
	s_cbranch_scc0 .LBB0_1038
	v_readlane_b32 s0, v251, 54
	v_readlane_b32 s1, v251, 55
	s_and_b64 vcc, exec, s[0:1]
	s_cbranch_vccz .LBB0_1041
	s_barrier

.LBB0_1265:
	s_add_u32 s35, s42, 0xffe00080
	s_addc_u32 s44, s43, -1
	s_add_i32 s54, 0, 0x10000
	s_cmpk_eq_i32 s33, 0x7c
	s_cselect_b32 s53, s12, s44
	s_cselect_b32 s52, s17, s35
	v_add_u32_e32 v148, s54, v153
	s_cselect_b32 s45, s5, s28
	s_cselect_b32 s44, s18, s20
	s_add_i32 s35, 0, 0x14000
	ds_read_b128 v[144:147], v148
	ds_read_b128 v[154:157], v148 offset:1024
	ds_read_b128 v[160:163], v148 offset:2048
	ds_read_b128 v[164:167], v148 offset:3072
	v_add_u32_e32 v148, s35, v153
	ds_read_b128 v[168:171], v148
	ds_read_b128 v[172:175], v148 offset:1024
	ds_read_b128 v[176:179], v148 offset:2048
	ds_read_b128 v[180:183], v148 offset:3072
	v_lshl_add_u64 v[148:149], s[42:43], 0, v[140:141]
	s_add_i32 m0, s59, 0xc000
	ds_read_b128 v[184:187], v159
	ds_read_b128 v[188:191], v159 offset:1024
	ds_read_b128 v[192:195], v159 offset:2048
	ds_read_b128 v[196:199], v159 offset:3072
	ds_read_b128 v[202:205], v159 offset:4096
	ds_read_b128 v[210:213], v159 offset:5120
	ds_read_b128 v[214:217], v159 offset:6144
	ds_read_b128 v[218:221], v159 offset:7168
	global_load_lds_dwordx4 v[148:149], off
	v_lshl_add_u64 v[148:149], s[42:43], 0, v[142:143]
	s_add_i32 m0, s59, 0xe000
	s_nop 0
	global_load_lds_dwordx4 v[148:149], off
	s_waitcnt vmcnt(8)
	s_waitcnt lgkmcnt(0)
	s_setprio 1
	s_barrier
	v_mfma_f32_16x16x32_bf16 v[126:129], v[144:147], v[184:187], v[126:129]
	v_mfma_f32_16x16x32_bf16 v[122:125], v[160:163], v[184:187], v[122:125]
	v_mfma_f32_16x16x32_bf16 v[110:113], v[144:147], v[192:195], v[110:113]
	v_mfma_f32_16x16x32_bf16 v[106:109], v[160:163], v[192:195], v[106:109]
	v_mfma_f32_16x16x32_bf16 v[92:95], v[144:147], v[202:205], v[92:95]
	v_mfma_f32_16x16x32_bf16 v[88:91], v[160:163], v[202:205], v[88:91]
	v_mfma_f32_16x16x32_bf16 v[76:79], v[144:147], v[214:217], v[76:79]
	v_mfma_f32_16x16x32_bf16 v[72:75], v[160:163], v[214:217], v[72:75]
	v_mfma_f32_16x16x32_bf16 v[126:129], v[154:157], v[188:191], v[126:129]
	v_mfma_f32_16x16x32_bf16 v[122:125], v[164:167], v[188:191], v[122:125]
	v_mfma_f32_16x16x32_bf16 v[110:113], v[154:157], v[196:199], v[110:113]
	v_mfma_f32_16x16x32_bf16 v[106:109], v[164:167], v[196:199], v[106:109]
	v_mfma_f32_16x16x32_bf16 v[92:95], v[154:157], v[210:213], v[92:95]
	v_mfma_f32_16x16x32_bf16 v[88:91], v[164:167], v[210:213], v[88:91]
	v_mfma_f32_16x16x32_bf16 v[76:79], v[154:157], v[218:221], v[76:79]
	v_mfma_f32_16x16x32_bf16 v[72:75], v[164:167], v[218:221], v[72:75]
	v_mfma_f32_16x16x32_bf16 v[118:121], v[168:171], v[184:187], v[118:121]
	v_mfma_f32_16x16x32_bf16 v[114:117], v[176:179], v[184:187], v[114:117]
	v_mfma_f32_16x16x32_bf16 v[102:105], v[168:171], v[192:195], v[102:105]
	v_mfma_f32_16x16x32_bf16 v[98:101], v[176:179], v[192:195], v[98:101]
	v_mfma_f32_16x16x32_bf16 v[84:87], v[168:171], v[202:205], v[84:87]
	v_mfma_f32_16x16x32_bf16 v[80:83], v[176:179], v[202:205], v[80:83]
	v_mfma_f32_16x16x32_bf16 v[68:71], v[168:171], v[214:217], v[68:71]
	v_mfma_f32_16x16x32_bf16 v[64:67], v[176:179], v[214:217], v[64:67]
	v_mfma_f32_16x16x32_bf16 v[118:121], v[172:175], v[188:191], v[118:121]
	v_mfma_f32_16x16x32_bf16 v[114:117], v[180:183], v[188:191], v[114:117]
	v_mfma_f32_16x16x32_bf16 v[102:105], v[172:175], v[196:199], v[102:105]
	v_mfma_f32_16x16x32_bf16 v[98:101], v[180:183], v[196:199], v[98:101]
	v_mfma_f32_16x16x32_bf16 v[84:87], v[172:175], v[210:213], v[84:87]
	v_mfma_f32_16x16x32_bf16 v[80:83], v[180:183], v[210:213], v[80:83]
	v_mfma_f32_16x16x32_bf16 v[68:71], v[172:175], v[218:221], v[68:71]
	v_mfma_f32_16x16x32_bf16 v[64:67], v[180:183], v[218:221], v[64:67]
	s_barrier
	s_setprio 0
	s_add_i32 s54, s54, s75
	v_lshl_add_u64 v[148:149], s[44:45], 0, v[96:97]
	s_mov_b32 m0, s54
	ds_read_b128 v[184:187], v159 offset:16384
	ds_read_b128 v[188:191], v159 offset:17408
	ds_read_b128 v[192:195], v159 offset:18432
	ds_read_b128 v[196:199], v159 offset:19456
	ds_read_b128 v[202:205], v159 offset:20480
	ds_read_b128 v[210:213], v159 offset:21504
	ds_read_b128 v[214:217], v159 offset:22528
	ds_read_b128 v[218:221], v159 offset:23552
	global_load_lds_dwordx4 v[148:149], off
	s_add_i32 m0, s54, 0x2000
	s_add_u32 s54, s44, 0x200000
	v_lshl_add_u64 v[222:223], s[44:45], 0, v[134:135]
	s_addc_u32 s55, s45, 0
	s_add_i32 s35, s35, s75
	global_load_lds_dwordx4 v[222:223], off
	v_lshl_add_u64 v[224:225], s[54:55], 0, v[96:97]
	s_mov_b32 m0, s35
	v_lshl_add_u64 v[226:227], s[52:53], 0, v[136:137]
	global_load_lds_dwordx4 v[224:225], off
	v_lshl_add_u64 v[224:225], s[54:55], 0, v[134:135]
	s_add_i32 m0, s35, 0x2000
	s_nop 0
	global_load_lds_dwordx4 v[224:225], off
	v_lshl_add_u64 v[224:225], s[52:53], 0, v[138:139]
	s_mov_b32 m0, s59
	s_nop 0
	global_load_lds_dwordx4 v[224:225], off
	s_mov_b32 m0, s68
	s_nop 0
	global_load_lds_dwordx4 v[226:227], off
	s_waitcnt vmcnt(8)
	s_waitcnt lgkmcnt(0)
	s_setprio 1
	s_barrier
	v_mfma_f32_16x16x32_bf16 v[60:63], v[144:147], v[184:187], v[60:63]
	v_mfma_f32_16x16x32_bf16 v[56:59], v[160:163], v[184:187], v[56:59]
	v_mfma_f32_16x16x32_bf16 v[44:47], v[144:147], v[192:195], v[44:47]
	v_mfma_f32_16x16x32_bf16 v[40:43], v[160:163], v[192:195], v[40:43]
	v_mfma_f32_16x16x32_bf16 v[28:31], v[144:147], v[202:205], v[28:31]
	v_mfma_f32_16x16x32_bf16 v[24:27], v[160:163], v[202:205], v[24:27]
	v_mfma_f32_16x16x32_bf16 v[12:15], v[144:147], v[214:217], v[12:15]
	v_mfma_f32_16x16x32_bf16 v[8:11], v[160:163], v[214:217], v[8:11]
	v_mfma_f32_16x16x32_bf16 v[60:63], v[154:157], v[188:191], v[60:63]
	v_mfma_f32_16x16x32_bf16 v[56:59], v[164:167], v[188:191], v[56:59]
	v_mfma_f32_16x16x32_bf16 v[44:47], v[154:157], v[196:199], v[44:47]
	v_mfma_f32_16x16x32_bf16 v[40:43], v[164:167], v[196:199], v[40:43]
	v_mfma_f32_16x16x32_bf16 v[28:31], v[154:157], v[210:213], v[28:31]
	v_mfma_f32_16x16x32_bf16 v[24:27], v[164:167], v[210:213], v[24:27]
	v_mfma_f32_16x16x32_bf16 v[12:15], v[154:157], v[218:221], v[12:15]
	v_mfma_f32_16x16x32_bf16 v[8:11], v[164:167], v[218:221], v[8:11]
	v_mfma_f32_16x16x32_bf16 v[52:55], v[168:171], v[184:187], v[52:55]
	v_mfma_f32_16x16x32_bf16 v[48:51], v[176:179], v[184:187], v[48:51]
	v_mfma_f32_16x16x32_bf16 v[36:39], v[168:171], v[192:195], v[36:39]
	v_mfma_f32_16x16x32_bf16 v[32:35], v[176:179], v[192:195], v[32:35]
	v_mfma_f32_16x16x32_bf16 v[20:23], v[168:171], v[202:205], v[20:23]
	v_mfma_f32_16x16x32_bf16 v[16:19], v[176:179], v[202:205], v[16:19]
	v_mfma_f32_16x16x32_bf16 v[4:7], v[168:171], v[214:217], v[4:7]
	v_mfma_f32_16x16x32_bf16 v[0:3], v[176:179], v[214:217], v[0:3]
	v_mfma_f32_16x16x32_bf16 v[52:55], v[172:175], v[188:191], v[52:55]
	v_mfma_f32_16x16x32_bf16 v[48:51], v[180:183], v[188:191], v[48:51]
	v_mfma_f32_16x16x32_bf16 v[36:39], v[172:175], v[196:199], v[36:39]
	v_mfma_f32_16x16x32_bf16 v[32:35], v[180:183], v[196:199], v[32:35]
	v_mfma_f32_16x16x32_bf16 v[20:23], v[172:175], v[210:213], v[20:23]
	v_mfma_f32_16x16x32_bf16 v[16:19], v[180:183], v[210:213], v[16:19]
	v_mfma_f32_16x16x32_bf16 v[4:7], v[172:175], v[218:221], v[4:7]
	v_mfma_f32_16x16x32_bf16 v[0:3], v[180:183], v[218:221], v[0:3]
	s_barrier
	s_setprio 0
	s_add_i32 s35, 0, 0x18000
	s_add_i32 s54, 0, 0x1c000
	v_add_u32_e32 v164, s35, v153
	v_add_u32_e32 v180, s54, v153
	ds_read_b128 v[144:147], v164
	ds_read_b128 v[154:157], v164 offset:1024
	ds_read_b128 v[160:163], v164 offset:2048
	ds_read_b128 v[164:167], v164 offset:3072
	ds_read_b128 v[168:171], v180
	ds_read_b128 v[172:175], v180 offset:1024
	ds_read_b128 v[176:179], v180 offset:2048
	ds_read_b128 v[180:183], v180 offset:3072
	s_add_u32 s52, s52, 0x200000
	s_addc_u32 s53, s53, 0
	s_mov_b32 m0, s69
	v_lshl_add_u64 v[228:229], s[52:53], 0, v[138:139]
	ds_read_b128 v[184:187], v159 offset:32768
	ds_read_b128 v[188:191], v159 offset:33792
	ds_read_b128 v[192:195], v159 offset:34816
	ds_read_b128 v[196:199], v159 offset:35840
	ds_read_b128 v[202:205], v159 offset:36864
	ds_read_b128 v[210:213], v159 offset:37888
	ds_read_b128 v[214:217], v159 offset:38912
	ds_read_b128 v[218:221], v159 offset:39936
	global_load_lds_dwordx4 v[228:229], off
	v_lshl_add_u64 v[228:229], s[52:53], 0, v[136:137]
	s_mov_b32 m0, s79
	s_nop 0
	global_load_lds_dwordx4 v[228:229], off
	s_waitcnt vmcnt(8)
	s_waitcnt lgkmcnt(0)
	s_setprio 1
	s_barrier
	v_mfma_f32_16x16x32_bf16 v[126:129], v[144:147], v[184:187], v[126:129]
	v_mfma_f32_16x16x32_bf16 v[122:125], v[160:163], v[184:187], v[122:125]
	v_mfma_f32_16x16x32_bf16 v[110:113], v[144:147], v[192:195], v[110:113]
	v_mfma_f32_16x16x32_bf16 v[106:109], v[160:163], v[192:195], v[106:109]
	v_mfma_f32_16x16x32_bf16 v[92:95], v[144:147], v[202:205], v[92:95]
	v_mfma_f32_16x16x32_bf16 v[88:91], v[160:163], v[202:205], v[88:91]
	v_mfma_f32_16x16x32_bf16 v[76:79], v[144:147], v[214:217], v[76:79]
	v_mfma_f32_16x16x32_bf16 v[72:75], v[160:163], v[214:217], v[72:75]
	v_mfma_f32_16x16x32_bf16 v[126:129], v[154:157], v[188:191], v[126:129]
	v_mfma_f32_16x16x32_bf16 v[122:125], v[164:167], v[188:191], v[122:125]
	v_mfma_f32_16x16x32_bf16 v[110:113], v[154:157], v[196:199], v[110:113]
	v_mfma_f32_16x16x32_bf16 v[106:109], v[164:167], v[196:199], v[106:109]
	v_mfma_f32_16x16x32_bf16 v[92:95], v[154:157], v[210:213], v[92:95]
	v_mfma_f32_16x16x32_bf16 v[88:91], v[164:167], v[210:213], v[88:91]
	v_mfma_f32_16x16x32_bf16 v[76:79], v[154:157], v[218:221], v[76:79]
	v_mfma_f32_16x16x32_bf16 v[72:75], v[164:167], v[218:221], v[72:75]
	v_mfma_f32_16x16x32_bf16 v[118:121], v[168:171], v[184:187], v[118:121]
	v_mfma_f32_16x16x32_bf16 v[114:117], v[176:179], v[184:187], v[114:117]
	v_mfma_f32_16x16x32_bf16 v[102:105], v[168:171], v[192:195], v[102:105]
	v_mfma_f32_16x16x32_bf16 v[98:101], v[176:179], v[192:195], v[98:101]
	v_mfma_f32_16x16x32_bf16 v[84:87], v[168:171], v[202:205], v[84:87]
	v_mfma_f32_16x16x32_bf16 v[80:83], v[176:179], v[202:205], v[80:83]
	v_mfma_f32_16x16x32_bf16 v[68:71], v[168:171], v[214:217], v[68:71]
	v_mfma_f32_16x16x32_bf16 v[64:67], v[176:179], v[214:217], v[64:67]
	v_mfma_f32_16x16x32_bf16 v[118:121], v[172:175], v[188:191], v[118:121]
	v_mfma_f32_16x16x32_bf16 v[114:117], v[180:183], v[188:191], v[114:117]
	v_mfma_f32_16x16x32_bf16 v[102:105], v[172:175], v[196:199], v[102:105]
	v_mfma_f32_16x16x32_bf16 v[98:101], v[180:183], v[196:199], v[98:101]
	v_mfma_f32_16x16x32_bf16 v[84:87], v[172:175], v[210:213], v[84:87]
	v_mfma_f32_16x16x32_bf16 v[80:83], v[180:183], v[210:213], v[80:83]
	v_mfma_f32_16x16x32_bf16 v[68:71], v[172:175], v[218:221], v[68:71]
	v_mfma_f32_16x16x32_bf16 v[64:67], v[180:183], v[218:221], v[64:67]
	s_barrier
	s_setprio 0
	s_add_i32 s35, s35, s75
	v_lshl_add_u64 v[148:149], v[148:149], 0, s[64:65]
	s_mov_b32 m0, s35
	ds_read_b128 v[184:187], v159 offset:49152
	ds_read_b128 v[188:191], v159 offset:50176
	ds_read_b128 v[192:195], v159 offset:51200
	ds_read_b128 v[196:199], v159 offset:52224
	ds_read_b128 v[202:205], v159 offset:53248
	ds_read_b128 v[210:213], v159 offset:54272
	ds_read_b128 v[214:217], v159 offset:55296
	ds_read_b128 v[218:221], v159 offset:56320
	global_load_lds_dwordx4 v[148:149], off
	s_add_i32 m0, s35, 0x2000
	s_add_u32 s44, s44, 0x200080
	v_lshl_add_u64 v[148:149], v[222:223], 0, s[64:65]
	s_addc_u32 s45, s45, 0
	s_add_i32 s35, s54, s75
	global_load_lds_dwordx4 v[148:149], off
	v_lshl_add_u64 v[148:149], s[44:45], 0, v[96:97]
	s_mov_b32 m0, s35
	s_nop 0
	global_load_lds_dwordx4 v[148:149], off
	v_lshl_add_u64 v[148:149], s[44:45], 0, v[134:135]
	s_add_i32 m0, s35, 0x2000
	s_nop 0
	global_load_lds_dwordx4 v[148:149], off
	v_lshl_add_u64 v[148:149], v[224:225], 0, s[64:65]
	s_mov_b32 m0, s10
	s_nop 0
	global_load_lds_dwordx4 v[148:149], off
	v_lshl_add_u64 v[148:149], v[226:227], 0, s[64:65]
	s_mov_b32 m0, s77
	s_nop 0
	global_load_lds_dwordx4 v[148:149], off
	s_waitcnt vmcnt(8)
	s_waitcnt lgkmcnt(0)
	s_setprio 1
	s_barrier
	v_mfma_f32_16x16x32_bf16 v[60:63], v[144:147], v[184:187], v[60:63]
	v_mfma_f32_16x16x32_bf16 v[56:59], v[160:163], v[184:187], v[56:59]
	v_mfma_f32_16x16x32_bf16 v[44:47], v[144:147], v[192:195], v[44:47]
	v_mfma_f32_16x16x32_bf16 v[40:43], v[160:163], v[192:195], v[40:43]
	v_mfma_f32_16x16x32_bf16 v[28:31], v[144:147], v[202:205], v[28:31]
	v_mfma_f32_16x16x32_bf16 v[24:27], v[160:163], v[202:205], v[24:27]
	v_mfma_f32_16x16x32_bf16 v[12:15], v[144:147], v[214:217], v[12:15]
	v_mfma_f32_16x16x32_bf16 v[8:11], v[160:163], v[214:217], v[8:11]
	v_mfma_f32_16x16x32_bf16 v[60:63], v[154:157], v[188:191], v[60:63]
	v_mfma_f32_16x16x32_bf16 v[56:59], v[164:167], v[188:191], v[56:59]
	v_mfma_f32_16x16x32_bf16 v[44:47], v[154:157], v[196:199], v[44:47]
	v_mfma_f32_16x16x32_bf16 v[40:43], v[164:167], v[196:199], v[40:43]
	v_mfma_f32_16x16x32_bf16 v[28:31], v[154:157], v[210:213], v[28:31]
	v_mfma_f32_16x16x32_bf16 v[24:27], v[164:167], v[210:213], v[24:27]
	v_mfma_f32_16x16x32_bf16 v[12:15], v[154:157], v[218:221], v[12:15]
	v_mfma_f32_16x16x32_bf16 v[8:11], v[164:167], v[218:221], v[8:11]
	v_mfma_f32_16x16x32_bf16 v[52:55], v[168:171], v[184:187], v[52:55]
	v_mfma_f32_16x16x32_bf16 v[48:51], v[176:179], v[184:187], v[48:51]
	v_mfma_f32_16x16x32_bf16 v[36:39], v[168:171], v[192:195], v[36:39]
	v_mfma_f32_16x16x32_bf16 v[32:35], v[176:179], v[192:195], v[32:35]
	v_mfma_f32_16x16x32_bf16 v[20:23], v[168:171], v[202:205], v[20:23]
	v_mfma_f32_16x16x32_bf16 v[16:19], v[176:179], v[202:205], v[16:19]
	v_mfma_f32_16x16x32_bf16 v[4:7], v[168:171], v[214:217], v[4:7]
	v_mfma_f32_16x16x32_bf16 v[0:3], v[176:179], v[214:217], v[0:3]
	v_mfma_f32_16x16x32_bf16 v[52:55], v[172:175], v[188:191], v[52:55]
	v_mfma_f32_16x16x32_bf16 v[48:51], v[180:183], v[188:191], v[48:51]
	v_mfma_f32_16x16x32_bf16 v[36:39], v[172:175], v[196:199], v[36:39]
	v_mfma_f32_16x16x32_bf16 v[32:35], v[180:183], v[196:199], v[32:35]
	v_mfma_f32_16x16x32_bf16 v[20:23], v[172:175], v[210:213], v[20:23]
	v_mfma_f32_16x16x32_bf16 v[16:19], v[180:183], v[210:213], v[16:19]
	v_mfma_f32_16x16x32_bf16 v[4:7], v[172:175], v[218:221], v[4:7]
	v_mfma_f32_16x16x32_bf16 v[0:3], v[180:183], v[218:221], v[0:3]
	s_barrier
	s_setprio 0
	s_add_i32 s33, s33, 2
	s_add_u32 s42, s42, 0x100
	s_addc_u32 s43, s43, 0
	s_add_u32 s20, s20, 0x100
	s_addc_u32 s28, s28, 0
	s_cmpk_gt_u32 s33, 0x7d
	s_cbranch_scc0 .LBB0_1265
	v_readlane_b32 s6, v251, 54
	v_readlane_b32 s7, v251, 55
	s_and_b64 vcc, exec, s[6:7]
	s_movk_i32 s53, 0x6000
	s_cbranch_vccz .LBB0_1268
	s_barrier

.LBB0_1284:
	s_add_u32 s33, s52, 0xfff80080
	s_addc_u32 s38, s53, -1
	s_add_i32 s39, 0, 0x10000
	s_cmp_eq_u32 s28, 28
	s_cselect_b32 s83, s3, s38
	s_cselect_b32 s82, s12, s33
	v_add_u32_e32 v144, s39, v150
	s_cselect_b32 s69, s17, s25
	s_cselect_b32 s68, s18, s20
	s_add_i32 s33, 0, 0x14000
	ds_read_b128 v[154:157], v144
	ds_read_b128 v[158:161], v144 offset:1024
	ds_read_b128 v[162:165], v144 offset:2048
	ds_read_b128 v[166:169], v144 offset:3072
	v_add_u32_e32 v144, s33, v150
	ds_read_b128 v[170:173], v144
	ds_read_b128 v[174:177], v144 offset:1024
	ds_read_b128 v[178:181], v144 offset:2048
	ds_read_b128 v[182:185], v144 offset:3072
	v_lshl_add_u64 v[144:145], s[52:53], 0, v[140:141]
	s_add_i32 m0, s34, 0xc000
	ds_read_b128 v[186:189], v152
	ds_read_b128 v[190:193], v152 offset:1024
	ds_read_b128 v[194:197], v152 offset:2048
	ds_read_b128 v[202:205], v152 offset:3072
	ds_read_b128 v[210:213], v152 offset:4096
	ds_read_b128 v[214:217], v152 offset:5120
	ds_read_b128 v[218:221], v152 offset:6144
	ds_read_b128 v[222:225], v152 offset:7168
	global_load_lds_dwordx4 v[144:145], off
	v_lshl_add_u64 v[144:145], s[52:53], 0, v[142:143]
	s_add_i32 m0, s34, 0xe000
	s_nop 0
	global_load_lds_dwordx4 v[144:145], off
	s_waitcnt vmcnt(8)
	s_waitcnt lgkmcnt(0)
	s_setprio 1
	s_barrier
	v_mfma_f32_16x16x32_bf16 v[126:129], v[154:157], v[186:189], v[126:129]
	v_mfma_f32_16x16x32_bf16 v[122:125], v[162:165], v[186:189], v[122:125]
	v_mfma_f32_16x16x32_bf16 v[110:113], v[154:157], v[194:197], v[110:113]
	v_mfma_f32_16x16x32_bf16 v[106:109], v[162:165], v[194:197], v[106:109]
	v_mfma_f32_16x16x32_bf16 v[92:95], v[154:157], v[210:213], v[92:95]
	v_mfma_f32_16x16x32_bf16 v[88:91], v[162:165], v[210:213], v[88:91]
	v_mfma_f32_16x16x32_bf16 v[76:79], v[154:157], v[218:221], v[76:79]
	v_mfma_f32_16x16x32_bf16 v[72:75], v[162:165], v[218:221], v[72:75]
	v_mfma_f32_16x16x32_bf16 v[126:129], v[158:161], v[190:193], v[126:129]
	v_mfma_f32_16x16x32_bf16 v[122:125], v[166:169], v[190:193], v[122:125]
	v_mfma_f32_16x16x32_bf16 v[110:113], v[158:161], v[202:205], v[110:113]
	v_mfma_f32_16x16x32_bf16 v[106:109], v[166:169], v[202:205], v[106:109]
	v_mfma_f32_16x16x32_bf16 v[92:95], v[158:161], v[214:217], v[92:95]
	v_mfma_f32_16x16x32_bf16 v[88:91], v[166:169], v[214:217], v[88:91]
	v_mfma_f32_16x16x32_bf16 v[76:79], v[158:161], v[222:225], v[76:79]
	v_mfma_f32_16x16x32_bf16 v[72:75], v[166:169], v[222:225], v[72:75]
	v_mfma_f32_16x16x32_bf16 v[118:121], v[170:173], v[186:189], v[118:121]
	v_mfma_f32_16x16x32_bf16 v[114:117], v[178:181], v[186:189], v[114:117]
	v_mfma_f32_16x16x32_bf16 v[102:105], v[170:173], v[194:197], v[102:105]
	v_mfma_f32_16x16x32_bf16 v[98:101], v[178:181], v[194:197], v[98:101]
	v_mfma_f32_16x16x32_bf16 v[84:87], v[170:173], v[210:213], v[84:87]
	v_mfma_f32_16x16x32_bf16 v[80:83], v[178:181], v[210:213], v[80:83]
	v_mfma_f32_16x16x32_bf16 v[68:71], v[170:173], v[218:221], v[68:71]
	v_mfma_f32_16x16x32_bf16 v[64:67], v[178:181], v[218:221], v[64:67]
	v_mfma_f32_16x16x32_bf16 v[118:121], v[174:177], v[190:193], v[118:121]
	v_mfma_f32_16x16x32_bf16 v[114:117], v[182:185], v[190:193], v[114:117]
	v_mfma_f32_16x16x32_bf16 v[102:105], v[174:177], v[202:205], v[102:105]
	v_mfma_f32_16x16x32_bf16 v[98:101], v[182:185], v[202:205], v[98:101]
	v_mfma_f32_16x16x32_bf16 v[84:87], v[174:177], v[214:217], v[84:87]
	v_mfma_f32_16x16x32_bf16 v[80:83], v[182:185], v[214:217], v[80:83]
	v_mfma_f32_16x16x32_bf16 v[68:71], v[174:177], v[222:225], v[68:71]
	v_mfma_f32_16x16x32_bf16 v[64:67], v[182:185], v[222:225], v[64:67]
	s_barrier
	s_setprio 0
	s_add_i32 s38, s39, s75
	v_lshl_add_u64 v[144:145], s[68:69], 0, v[96:97]
	s_mov_b32 m0, s38
	ds_read_b128 v[186:189], v152 offset:16384
	ds_read_b128 v[190:193], v152 offset:17408
	ds_read_b128 v[194:197], v152 offset:18432
	ds_read_b128 v[202:205], v152 offset:19456
	ds_read_b128 v[210:213], v152 offset:20480
	ds_read_b128 v[214:217], v152 offset:21504
	ds_read_b128 v[218:221], v152 offset:22528
	ds_read_b128 v[222:225], v152 offset:23552
	global_load_lds_dwordx4 v[144:145], off
	s_add_i32 m0, s38, 0x2000
	s_add_u32 s38, s68, 0x80000
	v_lshl_add_u64 v[198:199], s[68:69], 0, v[134:135]
	s_addc_u32 s39, s69, 0
	s_add_i32 s33, s33, s75
	global_load_lds_dwordx4 v[198:199], off
	v_lshl_add_u64 v[226:227], s[38:39], 0, v[96:97]
	s_mov_b32 m0, s33
	v_lshl_add_u64 v[228:229], s[82:83], 0, v[136:137]
	global_load_lds_dwordx4 v[226:227], off
	v_lshl_add_u64 v[226:227], s[38:39], 0, v[134:135]
	s_add_i32 m0, s33, 0x2000
	s_nop 0
	global_load_lds_dwordx4 v[226:227], off
	v_lshl_add_u64 v[226:227], s[82:83], 0, v[138:139]
	s_mov_b32 m0, s34
	s_nop 0
	global_load_lds_dwordx4 v[226:227], off
	s_mov_b32 m0, s35
	s_nop 0
	global_load_lds_dwordx4 v[228:229], off
	s_waitcnt vmcnt(8)
	s_waitcnt lgkmcnt(0)
	s_setprio 1
	s_barrier
	v_mfma_f32_16x16x32_bf16 v[60:63], v[154:157], v[186:189], v[60:63]
	v_mfma_f32_16x16x32_bf16 v[56:59], v[162:165], v[186:189], v[56:59]
	v_mfma_f32_16x16x32_bf16 v[44:47], v[154:157], v[194:197], v[44:47]
	v_mfma_f32_16x16x32_bf16 v[40:43], v[162:165], v[194:197], v[40:43]
	v_mfma_f32_16x16x32_bf16 v[28:31], v[154:157], v[210:213], v[28:31]
	v_mfma_f32_16x16x32_bf16 v[24:27], v[162:165], v[210:213], v[24:27]
	v_mfma_f32_16x16x32_bf16 v[12:15], v[154:157], v[218:221], v[12:15]
	v_mfma_f32_16x16x32_bf16 v[8:11], v[162:165], v[218:221], v[8:11]
	v_mfma_f32_16x16x32_bf16 v[60:63], v[158:161], v[190:193], v[60:63]
	v_mfma_f32_16x16x32_bf16 v[56:59], v[166:169], v[190:193], v[56:59]
	v_mfma_f32_16x16x32_bf16 v[44:47], v[158:161], v[202:205], v[44:47]
	v_mfma_f32_16x16x32_bf16 v[40:43], v[166:169], v[202:205], v[40:43]
	v_mfma_f32_16x16x32_bf16 v[28:31], v[158:161], v[214:217], v[28:31]
	v_mfma_f32_16x16x32_bf16 v[24:27], v[166:169], v[214:217], v[24:27]
	v_mfma_f32_16x16x32_bf16 v[12:15], v[158:161], v[222:225], v[12:15]
	v_mfma_f32_16x16x32_bf16 v[8:11], v[166:169], v[222:225], v[8:11]
	v_mfma_f32_16x16x32_bf16 v[52:55], v[170:173], v[186:189], v[52:55]
	v_mfma_f32_16x16x32_bf16 v[48:51], v[178:181], v[186:189], v[48:51]
	v_mfma_f32_16x16x32_bf16 v[36:39], v[170:173], v[194:197], v[36:39]
	v_mfma_f32_16x16x32_bf16 v[32:35], v[178:181], v[194:197], v[32:35]
	v_mfma_f32_16x16x32_bf16 v[20:23], v[170:173], v[210:213], v[20:23]
	v_mfma_f32_16x16x32_bf16 v[16:19], v[178:181], v[210:213], v[16:19]
	v_mfma_f32_16x16x32_bf16 v[4:7], v[170:173], v[218:221], v[4:7]
	v_mfma_f32_16x16x32_bf16 v[0:3], v[178:181], v[218:221], v[0:3]
	v_mfma_f32_16x16x32_bf16 v[52:55], v[174:177], v[190:193], v[52:55]
	v_mfma_f32_16x16x32_bf16 v[48:51], v[182:185], v[190:193], v[48:51]
	v_mfma_f32_16x16x32_bf16 v[36:39], v[174:177], v[202:205], v[36:39]
	v_mfma_f32_16x16x32_bf16 v[32:35], v[182:185], v[202:205], v[32:35]
	v_mfma_f32_16x16x32_bf16 v[20:23], v[174:177], v[214:217], v[20:23]
	v_mfma_f32_16x16x32_bf16 v[16:19], v[182:185], v[214:217], v[16:19]
	v_mfma_f32_16x16x32_bf16 v[4:7], v[174:177], v[222:225], v[4:7]
	v_mfma_f32_16x16x32_bf16 v[0:3], v[182:185], v[222:225], v[0:3]
	s_barrier
	s_setprio 0
	s_add_i32 s33, 0, 0x18000
	v_add_u32_e32 v153, s33, v150
	s_add_i32 s54, 0, 0x1c000
	ds_read_b128 v[154:157], v153
	ds_read_b128 v[158:161], v153 offset:1024
	ds_read_b128 v[162:165], v153 offset:2048
	ds_read_b128 v[166:169], v153 offset:3072
	v_add_u32_e32 v153, s54, v150
	ds_read_b128 v[170:173], v153
	ds_read_b128 v[174:177], v153 offset:1024
	ds_read_b128 v[178:181], v153 offset:2048
	ds_read_b128 v[182:185], v153 offset:3072
	s_add_u32 s38, s82, 0x80000
	s_addc_u32 s39, s83, 0
	s_mov_b32 m0, s50
	v_lshl_add_u64 v[230:231], s[38:39], 0, v[138:139]
	ds_read_b128 v[186:189], v152 offset:32768
	ds_read_b128 v[190:193], v152 offset:33792
	ds_read_b128 v[194:197], v152 offset:34816
	ds_read_b128 v[202:205], v152 offset:35840
	ds_read_b128 v[210:213], v152 offset:36864
	ds_read_b128 v[214:217], v152 offset:37888
	ds_read_b128 v[218:221], v152 offset:38912
	ds_read_b128 v[222:225], v152 offset:39936
	global_load_lds_dwordx4 v[230:231], off
	v_lshl_add_u64 v[230:231], s[38:39], 0, v[136:137]
	s_mov_b32 m0, s51
	s_nop 0
	global_load_lds_dwordx4 v[230:231], off
	s_waitcnt vmcnt(8)
	s_waitcnt lgkmcnt(0)
	s_setprio 1
	s_barrier
	v_mfma_f32_16x16x32_bf16 v[126:129], v[154:157], v[186:189], v[126:129]
	v_mfma_f32_16x16x32_bf16 v[122:125], v[162:165], v[186:189], v[122:125]
	v_mfma_f32_16x16x32_bf16 v[110:113], v[154:157], v[194:197], v[110:113]
	v_mfma_f32_16x16x32_bf16 v[106:109], v[162:165], v[194:197], v[106:109]
	v_mfma_f32_16x16x32_bf16 v[92:95], v[154:157], v[210:213], v[92:95]
	v_mfma_f32_16x16x32_bf16 v[88:91], v[162:165], v[210:213], v[88:91]
	v_mfma_f32_16x16x32_bf16 v[76:79], v[154:157], v[218:221], v[76:79]
	v_mfma_f32_16x16x32_bf16 v[72:75], v[162:165], v[218:221], v[72:75]
	v_mfma_f32_16x16x32_bf16 v[126:129], v[158:161], v[190:193], v[126:129]
	v_mfma_f32_16x16x32_bf16 v[122:125], v[166:169], v[190:193], v[122:125]
	v_mfma_f32_16x16x32_bf16 v[110:113], v[158:161], v[202:205], v[110:113]
	v_mfma_f32_16x16x32_bf16 v[106:109], v[166:169], v[202:205], v[106:109]
	v_mfma_f32_16x16x32_bf16 v[92:95], v[158:161], v[214:217], v[92:95]
	v_mfma_f32_16x16x32_bf16 v[88:91], v[166:169], v[214:217], v[88:91]
	v_mfma_f32_16x16x32_bf16 v[76:79], v[158:161], v[222:225], v[76:79]
	v_mfma_f32_16x16x32_bf16 v[72:75], v[166:169], v[222:225], v[72:75]
	v_mfma_f32_16x16x32_bf16 v[118:121], v[170:173], v[186:189], v[118:121]
	v_mfma_f32_16x16x32_bf16 v[114:117], v[178:181], v[186:189], v[114:117]
	v_mfma_f32_16x16x32_bf16 v[102:105], v[170:173], v[194:197], v[102:105]
	v_mfma_f32_16x16x32_bf16 v[98:101], v[178:181], v[194:197], v[98:101]
	v_mfma_f32_16x16x32_bf16 v[84:87], v[170:173], v[210:213], v[84:87]
	v_mfma_f32_16x16x32_bf16 v[80:83], v[178:181], v[210:213], v[80:83]
	v_mfma_f32_16x16x32_bf16 v[68:71], v[170:173], v[218:221], v[68:71]
	v_mfma_f32_16x16x32_bf16 v[64:67], v[178:181], v[218:221], v[64:67]
	v_mfma_f32_16x16x32_bf16 v[118:121], v[174:177], v[190:193], v[118:121]
	v_mfma_f32_16x16x32_bf16 v[114:117], v[182:185], v[190:193], v[114:117]
	v_mfma_f32_16x16x32_bf16 v[102:105], v[174:177], v[202:205], v[102:105]
	v_mfma_f32_16x16x32_bf16 v[98:101], v[182:185], v[202:205], v[98:101]
	v_mfma_f32_16x16x32_bf16 v[84:87], v[174:177], v[214:217], v[84:87]
	v_mfma_f32_16x16x32_bf16 v[80:83], v[182:185], v[214:217], v[80:83]
	v_mfma_f32_16x16x32_bf16 v[68:71], v[174:177], v[222:225], v[68:71]
	v_mfma_f32_16x16x32_bf16 v[64:67], v[182:185], v[222:225], v[64:67]
	s_barrier
	s_setprio 0
	s_add_i32 s33, s33, s75
	v_lshl_add_u64 v[144:145], v[144:145], 0, s[64:65]
	s_mov_b32 m0, s33
	ds_read_b128 v[186:189], v152 offset:49152
	ds_read_b128 v[190:193], v152 offset:50176
	ds_read_b128 v[194:197], v152 offset:51200
	ds_read_b128 v[202:205], v152 offset:52224
	ds_read_b128 v[210:213], v152 offset:53248
	ds_read_b128 v[214:217], v152 offset:54272
	ds_read_b128 v[218:221], v152 offset:55296
	ds_read_b128 v[222:225], v152 offset:56320
	global_load_lds_dwordx4 v[144:145], off
	s_add_i32 m0, s33, 0x2000
	s_add_u32 s38, s68, 0x80080
	v_lshl_add_u64 v[144:145], v[198:199], 0, s[64:65]
	s_addc_u32 s39, s69, 0
	s_add_i32 s33, s54, s75
	global_load_lds_dwordx4 v[144:145], off
	v_lshl_add_u64 v[144:145], s[38:39], 0, v[96:97]
	s_mov_b32 m0, s33
	s_nop 0
	global_load_lds_dwordx4 v[144:145], off
	v_lshl_add_u64 v[144:145], s[38:39], 0, v[134:135]
	s_add_i32 m0, s33, 0x2000
	s_nop 0
	global_load_lds_dwordx4 v[144:145], off
	v_lshl_add_u64 v[144:145], v[226:227], 0, s[64:65]
	s_mov_b32 m0, s58
	s_nop 0
	global_load_lds_dwordx4 v[144:145], off
	v_lshl_add_u64 v[144:145], v[228:229], 0, s[64:65]
	s_mov_b32 m0, s59
	s_nop 0
	global_load_lds_dwordx4 v[144:145], off
	s_waitcnt vmcnt(8)
	s_waitcnt lgkmcnt(0)
	s_setprio 1
	s_barrier
	v_mfma_f32_16x16x32_bf16 v[60:63], v[154:157], v[186:189], v[60:63]
	v_mfma_f32_16x16x32_bf16 v[56:59], v[162:165], v[186:189], v[56:59]
	v_mfma_f32_16x16x32_bf16 v[44:47], v[154:157], v[194:197], v[44:47]
	v_mfma_f32_16x16x32_bf16 v[40:43], v[162:165], v[194:197], v[40:43]
	v_mfma_f32_16x16x32_bf16 v[28:31], v[154:157], v[210:213], v[28:31]
	v_mfma_f32_16x16x32_bf16 v[24:27], v[162:165], v[210:213], v[24:27]
	v_mfma_f32_16x16x32_bf16 v[12:15], v[154:157], v[218:221], v[12:15]
	v_mfma_f32_16x16x32_bf16 v[8:11], v[162:165], v[218:221], v[8:11]
	v_mfma_f32_16x16x32_bf16 v[60:63], v[158:161], v[190:193], v[60:63]
	v_mfma_f32_16x16x32_bf16 v[56:59], v[166:169], v[190:193], v[56:59]
	v_mfma_f32_16x16x32_bf16 v[44:47], v[158:161], v[202:205], v[44:47]
	v_mfma_f32_16x16x32_bf16 v[40:43], v[166:169], v[202:205], v[40:43]
	v_mfma_f32_16x16x32_bf16 v[28:31], v[158:161], v[214:217], v[28:31]
	v_mfma_f32_16x16x32_bf16 v[24:27], v[166:169], v[214:217], v[24:27]
	v_mfma_f32_16x16x32_bf16 v[12:15], v[158:161], v[222:225], v[12:15]
	v_mfma_f32_16x16x32_bf16 v[8:11], v[166:169], v[222:225], v[8:11]
	v_mfma_f32_16x16x32_bf16 v[52:55], v[170:173], v[186:189], v[52:55]
	v_mfma_f32_16x16x32_bf16 v[48:51], v[178:181], v[186:189], v[48:51]
	v_mfma_f32_16x16x32_bf16 v[36:39], v[170:173], v[194:197], v[36:39]
	v_mfma_f32_16x16x32_bf16 v[32:35], v[178:181], v[194:197], v[32:35]
	v_mfma_f32_16x16x32_bf16 v[20:23], v[170:173], v[210:213], v[20:23]
	v_mfma_f32_16x16x32_bf16 v[16:19], v[178:181], v[210:213], v[16:19]
	v_mfma_f32_16x16x32_bf16 v[4:7], v[170:173], v[218:221], v[4:7]
	v_mfma_f32_16x16x32_bf16 v[0:3], v[178:181], v[218:221], v[0:3]
	v_mfma_f32_16x16x32_bf16 v[52:55], v[174:177], v[190:193], v[52:55]
	v_mfma_f32_16x16x32_bf16 v[48:51], v[182:185], v[190:193], v[48:51]
	v_mfma_f32_16x16x32_bf16 v[36:39], v[174:177], v[202:205], v[36:39]
	v_mfma_f32_16x16x32_bf16 v[32:35], v[182:185], v[202:205], v[32:35]
	v_mfma_f32_16x16x32_bf16 v[20:23], v[174:177], v[214:217], v[20:23]
	v_mfma_f32_16x16x32_bf16 v[16:19], v[182:185], v[214:217], v[16:19]
	v_mfma_f32_16x16x32_bf16 v[4:7], v[174:177], v[222:225], v[4:7]
	v_mfma_f32_16x16x32_bf16 v[0:3], v[182:185], v[222:225], v[0:3]
	s_barrier
	s_setprio 0
	s_add_i32 s28, s28, 2
	s_add_u32 s52, s52, 0x100
	s_addc_u32 s53, s53, 0
	s_add_u32 s20, s20, 0x100
	s_addc_u32 s25, s25, 0
	s_cmp_gt_u32 s28, 29
	s_cbranch_scc0 .LBB0_1284
	v_readlane_b32 s6, v251, 54
	v_readlane_b32 s7, v251, 55
	s_and_b64 vcc, exec, s[6:7]
	s_cbranch_vccz .LBB0_1287
	s_barrier
